# prompt adaLN epilogue: packed-f32 dot products and a bank-conflict-free LDS layout of the weight vectors (on top of the transposing U reduction)
# baseline (speedup 1.0000x reference)
;     DEVI float* gw() const { return (float*)(ws + WS_GW); }
;     DEVI float* wsmall() const { return (float*)(ws + WS_WSMALL); }
; DEVI cfp_t inp(int i) { const __attribute__((address_space(4))) cfp_t* k = (const __attribute__((address_space(4))) cfp_t*)__builtin_amdgcn_kernarg_segment_ptr(); typedef const __attribute__((address_space(1))) float* gcfp_t; const gcfp_t r = *(const volatile __attribute__((address_space(4))) gcfp_t*)(k + i); return (cfp_t)r; }
; template <int WHICH> DEVI void adaln_apply(const P& p, int l, int r, int lane_in, float (&v)[16]) {
;     ...
;         const float* dtb = inp(16) + l * 8; const float* fb = inp(22) + l * 4;
;         const float* ws = p.wsmall() + (size_t)l * 12 * D + 16 * lane;
;         float dot[12];
; #pragma unroll
;         for (int jj = 0; jj < 12; ++jj) { float a = 0.f;
; #pragma unroll
;             for (int q = 0; q < 4; ++q) { const float4 w = *(const float4*)(ws + (size_t)jj * D + 4 * q); a += v[4 * q] * w.x + v[4 * q + 1] * w.y + v[4 * q + 2] * w.z + v[4 * q + 3] * w.w; }
; template <int WHICH> DEVI void adaln_rows(const P& p, int l, int gw, int NGW, int lane, bool from_inputs = false) {
;     const float* xp_ = from_inputs ? inp(0) : p.x(); const float* xs_ = from_inputs ? inp(1) - (size_t)M_P * D : p.x();
;     float4 nx[4];
;     if (gw < M) {
; #pragma unroll
;         for (int q = 0; q < 4; ++q) nx[q] = ((const float4*)((gw < M_P ? xp_ : xs_) + (size_t)gw * D + 16 * lane))[q]; }
.LBB0_95:
	v_mov_b32_e32 v227, 0xc600000
	v_mov_b32_e32 v226, 0xd622000
	s_cmp_lg_u32 s6, 0
	v_writelane_b32 v253, s6, 41
	s_cbranch_scc1 .LBB0_163
	v_readlane_b32 s6, v252, 3
	s_mov_b64 s[2:3], s[74:75]
	s_mov_b64 s[4:5], s[72:73]
	v_mov_b32_e32 v1, v210
	s_mov_b32 s10, s95
	s_mov_b32 s14, s6
	s_mov_b32 s6, s68
	s_load_dwordx2 s[6:7], s[0:1], 0x0
	s_load_dwordx2 s[8:9], s[0:1], 0x8
	s_cmpk_gt_i32 s14, 0x43ff
	s_cbranch_scc1 .LBB0_118
	v_mov_b32_e32 v218, s85
	v_lshrrev_b32_e32 v219, 2, v218
	v_sub_u32_e32 v218, v218, v219
	v_lshl_add_u32 v218, v210, 4, v218
	v_add_u32_e32 v220, 0x14100, v218
	v_add_u32_e32 v218, 0x1f812100, v218
	v_add_u32_e32 v219, 0x1000, v218
	global_load_dwordx4 v[124:127], v218, s[74:75] offset:0
	global_load_dwordx4 v[128:131], v218, s[74:75] offset:1024
	global_load_dwordx4 v[132:135], v218, s[74:75] offset:2048
	global_load_dwordx4 v[136:139], v218, s[74:75] offset:3072
	global_load_dwordx4 v[140:143], v219, s[74:75] offset:0
	global_load_dwordx4 v[144:147], v219, s[74:75] offset:1024
	v_mov_b32_e32 v192, s85
	v_lshrrev_b32_e32 v193, 2, v192
	v_sub_u32_e32 v192, v192, v193
	v_lshrrev_b32_e32 v192, 4, v192
	v_add_u32_e32 v192, v192, v210
	v_mov_b32_e32 v193, 0x14100
	v_add_u32_e32 v194, 0, v192
	v_lshrrev_b32_e32 v200, 8, v194
	v_and_b32_e32 v201, 3, v194
	v_bfe_u32 v194, v194, 2, 6
	v_lshl_add_u32 v200, v200, 2, v201
	v_lshl_add_u32 v194, v200, 6, v194
	v_lshl_add_u32 v194, v194, 4, v193
	v_add_u32_e32 v195, 64, v192
	v_lshrrev_b32_e32 v200, 8, v195
	v_and_b32_e32 v201, 3, v195
	v_bfe_u32 v195, v195, 2, 6
	v_lshl_add_u32 v200, v200, 2, v201
	v_lshl_add_u32 v195, v200, 6, v195
	v_lshl_add_u32 v195, v195, 4, v193
	v_add_u32_e32 v196, 128, v192
	v_lshrrev_b32_e32 v200, 8, v196
	v_and_b32_e32 v201, 3, v196
	v_bfe_u32 v196, v196, 2, 6
	v_lshl_add_u32 v200, v200, 2, v201
	v_lshl_add_u32 v196, v200, 6, v196
	v_lshl_add_u32 v196, v196, 4, v193
	v_add_u32_e32 v197, 192, v192
	v_lshrrev_b32_e32 v200, 8, v197
	v_and_b32_e32 v201, 3, v197
	v_bfe_u32 v197, v197, 2, 6
	v_lshl_add_u32 v200, v200, 2, v201
	v_lshl_add_u32 v197, v200, 6, v197
	v_lshl_add_u32 v197, v197, 4, v193
	v_add_u32_e32 v198, 256, v192
	v_lshrrev_b32_e32 v200, 8, v198
	v_and_b32_e32 v201, 3, v198
	v_bfe_u32 v198, v198, 2, 6
	v_lshl_add_u32 v200, v200, 2, v201
	v_lshl_add_u32 v198, v200, 6, v198
	v_lshl_add_u32 v198, v198, 4, v193
	v_add_u32_e32 v199, 320, v192
	v_lshrrev_b32_e32 v200, 8, v199
	v_and_b32_e32 v201, 3, v199
	v_bfe_u32 v199, v199, 2, 6
	v_lshl_add_u32 v200, v200, 2, v201
	v_lshl_add_u32 v199, v200, 6, v199
	v_lshl_add_u32 v199, v199, 4, v193
	s_waitcnt vmcnt(0)
	ds_write_b128 v194, v[124:127]
	ds_write_b128 v195, v[128:131]
	ds_write_b128 v196, v[132:135]
	ds_write_b128 v197, v[136:139]
	ds_write_b128 v198, v[140:143]
	ds_write_b128 v199, v[144:147]
	s_waitcnt lgkmcnt(0)
	s_barrier
	s_waitcnt lgkmcnt(0)
	s_add_u32 s26, s8, 0xfc000000
	s_addc_u32 s27, s9, -1
	s_cmpk_lt_i32 s14, 0x4000
	s_cselect_b32 s11, s7, s27
	s_cselect_b32 s12, s6, s26
	s_ashr_i32 s15, s14, 31
	s_lshl_b64 s[8:9], s[14:15], 12
	v_lshlrev_b32_e32 v2, 4, v1
	s_add_u32 s8, s12, s8
	v_ashrrev_i32_e32 v3, 31, v2
	s_addc_u32 s9, s11, s9
	v_lshlrev_b64 v[2:3], 2, v[2:3]
	v_lshl_add_u64 v[4:5], s[8:9], 0, v[2:3]
	global_load_dwordx4 v[34:37], v[4:5], off offset:48
	global_load_dwordx4 v[38:41], v[4:5], off offset:32
	global_load_dwordx4 v[42:45], v[4:5], off offset:16
	global_load_dwordx4 v[46:49], v[4:5], off
	s_waitcnt vmcnt(0)
	v_mov_b64_e32 v[10:11], s[2:3]
	v_mov_b32_e32 v12, 0xc000
	v_mad_i64_i32 v[6:7], s[8:9], s10, 18, 0
	v_mad_i64_i32 v[10:11], s[8:9], s10, v12, v[10:11]
	s_add_u32 s30, s2, 0x4000
	s_mov_b64 s[8:9], 0x1f812100
	s_addc_u32 s31, s3, 0
	v_lshl_add_u64 v[56:57], v[10:11], 0, s[8:9]
	s_lshl_b64 s[8:9], s[14:15], 5
	s_add_u32 s40, s8, 0xacda100
	v_ashrrev_i32_e64 v5, 31, s10
	v_mov_b32_e32 v4, s10
	s_addc_u32 s41, s9, 0
	s_add_i32 s12, s34, s14
	v_lshlrev_b64 v[54:55], 10, v[4:5]
	v_readfirstlane_b32 s28, v6
	v_lshlrev_b32_e64 v6, 2, s10
	v_lshlrev_b64 v[4:5], 18, v[4:5]
	v_lshlrev_b32_e64 v8, 3, s10
	s_ashr_i32 s13, s12, 31
	v_readfirstlane_b32 s29, v7
	v_ashrrev_i32_e32 v7, 31, v6
	v_ashrrev_i32_e32 v9, 31, v8
	v_lshl_add_u64 v[4:5], s[4:5], 0, v[4:5]
	s_mov_b64 s[10:11], 0xc400000
	s_lshl_b64 s[12:13], s[12:13], 12
	s_lshl_b64 s[8:9], s[14:15], 4
	v_lshl_add_u64 v[58:59], v[4:5], 0, s[10:11]
	s_lshl_b64 s[10:11], s[14:15], 11
	v_lshl_add_u64 v[60:61], s[12:13], 0, v[2:3]
	v_lshlrev_b64 v[62:63], 2, v[6:7]
	v_lshlrev_b64 v[64:65], 2, v[8:9]
	s_branch .LBB0_100

;     DEVI float* mod() const { return (float*)(ws + WS_MOD); }
; template <int WHICH> DEVI void adaln_apply(const P& p, int l, int r, int lane_in, float (&v)[16]) {
;     ...
;     float ss = 0.f;
; #pragma unroll
;     for (int i = 0; i < 16; ++i) ss += v[i] * v[i];
;     const float rstd = rsqrtf(wave_sum(ss) * (1.f / D) + EPS);
;     const float* md = p.mod() + ((size_t)l * NSEQ + row_seq(r)) * 6144 + 16 * lane;
; #pragma unroll
;     for (int q = 0; q < 4; ++q) {
;         const float4 gg = *(const float4*)(g + 4 * q), sc = *(const float4*)(md + osc + 4 * q), sh = *(const float4*)(md + osh + 4 * q);
;         v[4 * q] = v[4 * q] * rstd * gg.x * (1.f + sc.x) + sh.x; v[4 * q + 1] = v[4 * q + 1] * rstd * gg.y * (1.f + sc.y) + sh.y;
;         v[4 * q + 2] = v[4 * q + 2] * rstd * gg.z * (1.f + sc.z) + sh.z; v[4 * q + 3] = v[4 * q + 3] * rstd * gg.w * (1.f + sc.w) + sh.w;
;     }
;     u32x4_t* ob = (u32x4_t*)(p.hb() + (size_t)r * D + 16 * lane);
;     ob[0] = (u32x4_t){pk2bf(v[0], v[1]), pk2bf(v[2], v[3]), pk2bf(v[4], v[5]), pk2bf(v[6], v[7])};
;     ob[1] = (u32x4_t){pk2bf(v[8], v[9]), pk2bf(v[10], v[11]), pk2bf(v[12], v[13]), pk2bf(v[14], v[15])};
;     if constexpr (WHICH == 2) {
;         unsigned hi8[4], lo8[4];
; #pragma unroll
;         for (int q = 0; q < 4; ++q) { hi8[q] = pk4fp8(v[4 * q], v[4 * q + 1], v[4 * q + 2], v[4 * q + 3]);
;             const f32x2_t h01 = __builtin_amdgcn_cvt_pk_f32_fp8((int)hi8[q], false), h23 = __builtin_amdgcn_cvt_pk_f32_fp8((int)hi8[q], true);
;             lo8[q] = pk4fp8((v[4 * q] - h01[0]) * 32.f, (v[4 * q + 1] - h01[1]) * 32.f, (v[4 * q + 2] - h23[0]) * 32.f, (v[4 * q + 3] - h23[1]) * 32.f); }
;         *(u32x4_t*)(p.h8() + (size_t)r * D + 16 * lane) = (u32x4_t){hi8[0], hi8[1], hi8[2], hi8[3]};
;         *(u32x4_t*)(p.h8() + (size_t)M * D + (size_t)r * D + 16 * lane) = (u32x4_t){lo8[0], lo8[1], lo8[2], lo8[3]};
;     }
;     if constexpr (WHICH == 1) {
;         const float* dtb = inp(16) + l * 8; const float* fb = inp(22) + l * 4;
;         const float* ws = p.wsmall() + (size_t)l * 12 * D + 16 * lane;
;         float dot[12];
; #pragma unroll
;         for (int jj = 0; jj < 12; ++jj) { float a = 0.f;
; #pragma unroll
;             for (int q = 0; q < 4; ++q) { const float4 w = *(const float4*)(ws + (size_t)jj * D + 4 * q); a += v[4 * q] * w.x + v[4 * q + 1] * w.y + v[4 * q + 2] * w.z + v[4 * q + 3] * w.w; }
.LBB0_106:
	v_lshlrev_b64 v[18:19], 2, v[54:55]
	v_lshl_add_u64 v[18:19], s[18:19], 0, v[18:19]
	s_ashr_i32 s18, s15, 31
	s_add_u32 s15, s28, s15
	s_addc_u32 s18, s29, s18
	s_mulk_i32 s18, 0x6000
	s_mul_hi_u32 s19, s15, 0x6000
	v_lshlrev_b32_e32 v106, 4, v68
	s_add_i32 s19, s19, s18
	s_mulk_i32 s15, 0x6000
	v_ashrrev_i32_e32 v107, 31, v106
	s_add_u32 s18, s30, s15
	v_lshlrev_b64 v[50:51], 2, v[106:107]
	s_addc_u32 s19, s31, s19
	v_lshl_add_u64 v[18:19], v[18:19], 0, v[50:51]
	v_lshl_add_u64 v[22:23], s[18:19], 0, v[50:51]
	s_movk_i32 s15, 0x1000
	global_load_dwordx4 v[74:77], v[18:19], off offset:16
	global_load_dwordx4 v[78:81], v[18:19], off
	global_load_dwordx4 v[82:85], v[18:19], off offset:48
	global_load_dwordx4 v[86:89], v[18:19], off offset:32
	v_add_co_u32_e32 v18, vcc, s15, v22
	s_mov_b64 s[22:23], 0x1000
	s_nop 0
	v_addc_co_u32_e32 v19, vcc, 0, v23, vcc
	global_load_dwordx4 v[90:93], v[18:19], off
	v_lshl_add_u64 v[24:25], v[22:23], 0, s[22:23]
	global_load_dwordx4 v[94:97], v[24:25], off offset:16
	global_load_dwordx4 v[98:101], v[24:25], off offset:32
	global_load_dwordx4 v[30:33], v[22:23], off
	global_load_dwordx4 v[26:29], v[22:23], off offset:16
	global_load_dwordx4 v[18:21], v[22:23], off offset:32
	global_load_dwordx4 v[102:105], v[24:25], off offset:48
	s_nop 0
	global_load_dwordx4 v[22:25], v[22:23], off offset:48
	s_waitcnt lgkmcnt(0)
	v_add_f32_e32 v52, v52, v53
	v_fmamk_f32 v52, v52, 0x3a800000, v211
	s_mov_b32 s15, 0x800000
	v_mul_f32_e32 v53, 0x4b800000, v52
	v_cmp_gt_f32_e32 vcc, s15, v52
	s_add_u32 s18, s2, s10
	s_addc_u32 s19, s3, s11
	v_cndmask_b32_e32 v52, v52, v53, vcc
	v_rsq_f32_e32 v52, v52
	s_movk_i32 s15, 0x2000
	v_mul_f32_e32 v53, 0x45800000, v52
	v_cndmask_b32_e32 v52, v52, v53, vcc
	v_mul_f32_e32 v46, v46, v52
	v_mul_f32_e32 v42, v42, v52
	v_mul_f32_e32 v38, v38, v52
	v_mul_f32_e32 v34, v34, v52
	v_mul_f32_e32 v47, v47, v52
	v_mul_f32_e32 v43, v43, v52
	v_mul_f32_e32 v39, v39, v52
	v_mul_f32_e32 v48, v48, v52
	v_mul_f32_e32 v49, v49, v52
	v_mul_f32_e32 v44, v44, v52
	v_mul_f32_e32 v45, v45, v52
	v_mul_f32_e32 v40, v40, v52
	v_mul_f32_e32 v41, v41, v52
	s_waitcnt vmcnt(11)
	v_mul_f32_e32 v42, v42, v74
	s_waitcnt vmcnt(10)
	v_mul_f32_e32 v46, v46, v78
	s_waitcnt vmcnt(8)
	v_mul_f32_e32 v38, v38, v86
	v_mul_f32_e32 v34, v34, v82
	s_waitcnt vmcnt(6)
	v_add_f32_e32 v78, 1.0, v94
	s_waitcnt vmcnt(5)
	v_add_f32_e32 v82, 1.0, v98
	v_mul_f32_e32 v47, v47, v79
	v_mul_f32_e32 v43, v43, v75
	v_add_f32_e32 v53, 1.0, v90
	s_waitcnt vmcnt(4)
	v_fma_f32 v74, v46, v53, v30
	s_waitcnt vmcnt(3)
	v_fma_f32 v30, v42, v78, v26
	s_waitcnt vmcnt(2)
	v_fma_f32 v26, v38, v82, v18
	s_waitcnt vmcnt(1)
	v_add_f32_e32 v18, 1.0, v102
	v_mul_f32_e32 v39, v39, v87
	v_add_f32_e32 v75, 1.0, v91
	v_add_f32_e32 v79, 1.0, v95
	v_add_f32_e32 v86, 1.0, v99
	s_waitcnt vmcnt(0)
	v_fma_f32 v22, v34, v18, v22
	v_mul_f32_e32 v18, v35, v52
	v_fma_f32 v75, v47, v75, v31
	v_fma_f32 v31, v43, v79, v27
	v_fma_f32 v27, v39, v86, v19
	v_mul_f32_e32 v18, v18, v83
	v_add_f32_e32 v19, 1.0, v103
	v_fma_f32 v23, v18, v19, v23
	v_mul_f32_e32 v18, v36, v52
	v_mul_f32_e32 v18, v18, v84
	v_add_f32_e32 v19, 1.0, v104
	v_fma_f32 v24, v18, v19, v24
	v_mul_f32_e32 v18, v37, v52
	v_mul_f32_e32 v18, v18, v85
	v_add_f32_e32 v19, 1.0, v105
	v_fmac_f32_e32 v25, v18, v19
	v_lshl_add_u64 v[18:19], v[106:107], 1, s[18:19]
	v_mul_f32_e32 v48, v48, v80
	v_mul_f32_e32 v49, v49, v81
	v_mul_f32_e32 v44, v44, v76
	v_mul_f32_e32 v45, v45, v77
	v_add_f32_e32 v76, 1.0, v92
	v_add_f32_e32 v77, 1.0, v93
	v_add_f32_e32 v80, 1.0, v96
	v_add_f32_e32 v81, 1.0, v97
	v_add_co_u32_e32 v18, vcc, s82, v18
	v_mul_f32_e32 v40, v40, v88
	v_mul_f32_e32 v41, v41, v89
	v_add_f32_e32 v87, 1.0, v100
	v_add_f32_e32 v88, 1.0, v101
	v_fma_f32 v32, v48, v76, v32
	v_fmac_f32_e32 v33, v49, v77
	v_fma_f32 v28, v44, v80, v28
	v_fmac_f32_e32 v29, v45, v81
	v_cvt_pk_bf16_f32 v34, v74, v75
	v_cvt_pk_bf16_f32 v35, v32, v33
	v_cvt_pk_bf16_f32 v36, v30, v31
	v_cvt_pk_bf16_f32 v37, v28, v29
	v_addc_co_u32_e32 v19, vcc, 0, v19, vcc
	v_fma_f32 v20, v40, v87, v20
	v_fmac_f32_e32 v21, v41, v88
	global_store_dwordx4 v[18:19], v[34:37], off offset:256
	s_nop 1
	v_cvt_pk_bf16_f32 v34, v26, v27
	v_cvt_pk_bf16_f32 v35, v20, v21
	v_cvt_pk_bf16_f32 v36, v22, v23
	v_cvt_pk_bf16_f32 v37, v24, v25
	global_store_dwordx4 v[18:19], v[34:37], off offset:272
	v_mov_b32_e32 v219, 0x14100
	v_lshl_add_u32 v218, v68, 4, v219
	v_mov_b32_e32 v216, 0
	v_mov_b32_e32 v217, 0
	ds_read_b128 v[124:127], v218 offset:0
	ds_read_b128 v[128:131], v218 offset:1024
	ds_read_b128 v[132:135], v218 offset:2048
	ds_read_b128 v[136:139], v218 offset:3072
	ds_read_b128 v[140:143], v218 offset:4096
	ds_read_b128 v[144:147], v218 offset:5120
	ds_read_b128 v[148:151], v218 offset:6144
	ds_read_b128 v[152:155], v218 offset:7168
	ds_read_b128 v[156:159], v218 offset:8192
	ds_read_b128 v[160:163], v218 offset:9216
	ds_read_b128 v[164:167], v218 offset:10240
	ds_read_b128 v[168:171], v218 offset:11264
	ds_read_b128 v[172:175], v218 offset:12288
	ds_read_b128 v[180:183], v218 offset:13312
	ds_read_b128 v[184:187], v218 offset:14336
	ds_read_b128 v[188:191], v218 offset:15360
	s_waitcnt lgkmcnt(0)
;     DEVI float* wsmall() const { return (float*)(ws + WS_WSMALL); }
; template <int WHICH> DEVI void adaln_apply(const P& p, int l, int r, int lane_in, float (&v)[16]) {
;     ...
;         const float* ws = p.wsmall() + (size_t)l * 12 * D + 16 * lane;
;         float dot[12];
; #pragma unroll
;         for (int jj = 0; jj < 12; ++jj) { float a = 0.f;
; #pragma unroll
;             for (int q = 0; q < 4; ++q) { const float4 w = *(const float4*)(ws + (size_t)jj * D + 4 * q); a += v[4 * q] * w.x + v[4 * q + 1] * w.y + v[4 * q + 2] * w.z + v[4 * q + 3] * w.w; }
;             dot[jj] = wave_sum(a); }
	v_mul_f32_e32 v192, v74, v124
	v_mul_f32_e32 v193, v74, v140
	v_mul_f32_e32 v194, v74, v156
	v_mul_f32_e32 v195, v74, v172
	v_fmac_f32_e32 v192, v75, v125
	v_fmac_f32_e32 v193, v75, v141
	v_fmac_f32_e32 v194, v75, v157
	v_fmac_f32_e32 v195, v75, v173
	v_fmac_f32_e32 v192, v32, v126
	v_fmac_f32_e32 v193, v32, v142
	v_fmac_f32_e32 v194, v32, v158
	v_fmac_f32_e32 v195, v32, v174
	v_fmac_f32_e32 v192, v33, v127
	v_fmac_f32_e32 v193, v33, v143
	v_fmac_f32_e32 v194, v33, v159
	v_fmac_f32_e32 v195, v33, v175
	v_fmac_f32_e32 v192, v30, v128
	v_fmac_f32_e32 v193, v30, v144
	v_fmac_f32_e32 v194, v30, v160
	v_fmac_f32_e32 v195, v30, v180
	v_fmac_f32_e32 v192, v31, v129
	v_fmac_f32_e32 v193, v31, v145
	v_fmac_f32_e32 v194, v31, v161
	v_fmac_f32_e32 v195, v31, v181
	v_fmac_f32_e32 v192, v28, v130
	v_fmac_f32_e32 v193, v28, v146
	v_fmac_f32_e32 v194, v28, v162
	v_fmac_f32_e32 v195, v28, v182
	v_fmac_f32_e32 v192, v29, v131
	v_fmac_f32_e32 v193, v29, v147
	v_fmac_f32_e32 v194, v29, v163
	v_fmac_f32_e32 v195, v29, v183
	v_fmac_f32_e32 v192, v26, v132
	v_fmac_f32_e32 v193, v26, v148
	v_fmac_f32_e32 v194, v26, v164
	v_fmac_f32_e32 v195, v26, v184
	v_fmac_f32_e32 v192, v27, v133
	v_fmac_f32_e32 v193, v27, v149
	v_fmac_f32_e32 v194, v27, v165
	v_fmac_f32_e32 v195, v27, v185
	v_fmac_f32_e32 v192, v20, v134
	v_fmac_f32_e32 v193, v20, v150
	v_fmac_f32_e32 v194, v20, v166
	v_fmac_f32_e32 v195, v20, v186
	v_fmac_f32_e32 v192, v21, v135
	v_fmac_f32_e32 v193, v21, v151
	v_fmac_f32_e32 v194, v21, v167
	v_fmac_f32_e32 v195, v21, v187
	v_fmac_f32_e32 v192, v22, v136
	v_fmac_f32_e32 v193, v22, v152
	v_fmac_f32_e32 v194, v22, v168
	v_fmac_f32_e32 v195, v22, v188
	v_fmac_f32_e32 v192, v23, v137
	v_fmac_f32_e32 v193, v23, v153
	v_fmac_f32_e32 v194, v23, v169
	v_fmac_f32_e32 v195, v23, v189
	v_fmac_f32_e32 v192, v24, v138
	v_fmac_f32_e32 v193, v24, v154
	v_fmac_f32_e32 v194, v24, v170
	v_fmac_f32_e32 v195, v24, v190
	v_fmac_f32_e32 v192, v25, v139
	v_fmac_f32_e32 v193, v25, v155
	v_fmac_f32_e32 v194, v25, v171
	v_fmac_f32_e32 v195, v25, v191
	ds_read_b128 v[124:127], v218 offset:16384
	ds_read_b128 v[128:131], v218 offset:17408
	ds_read_b128 v[132:135], v218 offset:18432
	ds_read_b128 v[136:139], v218 offset:19456
	ds_read_b128 v[140:143], v218 offset:20480
	ds_read_b128 v[144:147], v218 offset:21504
	ds_read_b128 v[148:151], v218 offset:22528
	ds_read_b128 v[152:155], v218 offset:23552
	ds_read_b128 v[156:159], v218 offset:24576
	ds_read_b128 v[160:163], v218 offset:25600
	ds_read_b128 v[164:167], v218 offset:26624
	ds_read_b128 v[168:171], v218 offset:27648
	ds_read_b128 v[172:175], v218 offset:28672
	ds_read_b128 v[180:183], v218 offset:29696
	ds_read_b128 v[184:187], v218 offset:30720
	ds_read_b128 v[188:191], v218 offset:31744
	s_waitcnt lgkmcnt(0)
	v_mul_f32_e32 v196, v74, v124
	v_mul_f32_e32 v197, v74, v140
	v_mul_f32_e32 v198, v74, v156
	v_mul_f32_e32 v199, v74, v172
	v_fmac_f32_e32 v196, v75, v125
	v_fmac_f32_e32 v197, v75, v141
	v_fmac_f32_e32 v198, v75, v157
	v_fmac_f32_e32 v199, v75, v173
	v_fmac_f32_e32 v196, v32, v126
	v_fmac_f32_e32 v197, v32, v142
	v_fmac_f32_e32 v198, v32, v158
	v_fmac_f32_e32 v199, v32, v174
	v_fmac_f32_e32 v196, v33, v127
	v_fmac_f32_e32 v197, v33, v143
	v_fmac_f32_e32 v198, v33, v159
	v_fmac_f32_e32 v199, v33, v175
	v_fmac_f32_e32 v196, v30, v128
	v_fmac_f32_e32 v197, v30, v144
	v_fmac_f32_e32 v198, v30, v160
	v_fmac_f32_e32 v199, v30, v180
	v_fmac_f32_e32 v196, v31, v129
	v_fmac_f32_e32 v197, v31, v145
	v_fmac_f32_e32 v198, v31, v161
	v_fmac_f32_e32 v199, v31, v181
	v_fmac_f32_e32 v196, v28, v130
	v_fmac_f32_e32 v197, v28, v146
	v_fmac_f32_e32 v198, v28, v162
	v_fmac_f32_e32 v199, v28, v182
	v_fmac_f32_e32 v196, v29, v131
	v_fmac_f32_e32 v197, v29, v147
	v_fmac_f32_e32 v198, v29, v163
	v_fmac_f32_e32 v199, v29, v183
	v_fmac_f32_e32 v196, v26, v132
	v_fmac_f32_e32 v197, v26, v148
	v_fmac_f32_e32 v198, v26, v164
	v_fmac_f32_e32 v199, v26, v184
	v_fmac_f32_e32 v196, v27, v133
	v_fmac_f32_e32 v197, v27, v149
	v_fmac_f32_e32 v198, v27, v165
	v_fmac_f32_e32 v199, v27, v185
	v_fmac_f32_e32 v196, v20, v134
	v_fmac_f32_e32 v197, v20, v150
	v_fmac_f32_e32 v198, v20, v166
	v_fmac_f32_e32 v199, v20, v186
	v_fmac_f32_e32 v196, v21, v135
	v_fmac_f32_e32 v197, v21, v151
	v_fmac_f32_e32 v198, v21, v167
	v_fmac_f32_e32 v199, v21, v187
	v_fmac_f32_e32 v196, v22, v136
	v_fmac_f32_e32 v197, v22, v152
	v_fmac_f32_e32 v198, v22, v168
	v_fmac_f32_e32 v199, v22, v188
	v_fmac_f32_e32 v196, v23, v137
	v_fmac_f32_e32 v197, v23, v153
	v_fmac_f32_e32 v198, v23, v169
	v_fmac_f32_e32 v199, v23, v189
	v_fmac_f32_e32 v196, v24, v138
	v_fmac_f32_e32 v197, v24, v154
	v_fmac_f32_e32 v198, v24, v170
	v_fmac_f32_e32 v199, v24, v190
	v_fmac_f32_e32 v196, v25, v139
	v_fmac_f32_e32 v197, v25, v155
	v_fmac_f32_e32 v198, v25, v171
	v_fmac_f32_e32 v199, v25, v191
	ds_read_b128 v[124:127], v218 offset:32768
	ds_read_b128 v[128:131], v218 offset:33792
	ds_read_b128 v[132:135], v218 offset:34816
	ds_read_b128 v[136:139], v218 offset:35840
	ds_read_b128 v[140:143], v218 offset:36864
	ds_read_b128 v[144:147], v218 offset:37888
	ds_read_b128 v[148:151], v218 offset:38912
	ds_read_b128 v[152:155], v218 offset:39936
	ds_read_b128 v[156:159], v218 offset:40960
	ds_read_b128 v[160:163], v218 offset:41984
	ds_read_b128 v[164:167], v218 offset:43008
	ds_read_b128 v[168:171], v218 offset:44032
	ds_read_b128 v[172:175], v218 offset:45056
	ds_read_b128 v[180:183], v218 offset:46080
	ds_read_b128 v[184:187], v218 offset:47104
	ds_read_b128 v[188:191], v218 offset:48128
	s_waitcnt lgkmcnt(0)
; DEVI float wave_sum(float v) {
; #pragma unroll
;     for (int o = 1; o < 64; o <<= 1) v += __shfl_xor(v, o);
;     return v;
; }
; template <int WHICH> DEVI void adaln_apply(const P& p, int l, int r, int lane_in, float (&v)[16]) {
;     ...
;         for (int jj = 0; jj < 12; ++jj) { float a = 0.f;
; #pragma unroll
;             for (int q = 0; q < 4; ++q) { const float4 w = *(const float4*)(ws + (size_t)jj * D + 4 * q); a += v[4 * q] * w.x + v[4 * q + 1] * w.y + v[4 * q + 2] * w.z + v[4 * q + 3] * w.w; }
;             dot[jj] = wave_sum(a); }
	v_mul_f32_e32 v200, v74, v124
	v_mul_f32_e32 v201, v74, v140
	v_mul_f32_e32 v202, v74, v156
	v_mul_f32_e32 v203, v74, v172
	v_fmac_f32_e32 v200, v75, v125
	v_fmac_f32_e32 v201, v75, v141
	v_fmac_f32_e32 v202, v75, v157
	v_fmac_f32_e32 v203, v75, v173
	v_fmac_f32_e32 v200, v32, v126
	v_fmac_f32_e32 v201, v32, v142
	v_fmac_f32_e32 v202, v32, v158
	v_fmac_f32_e32 v203, v32, v174
	v_fmac_f32_e32 v200, v33, v127
	v_fmac_f32_e32 v201, v33, v143
	v_fmac_f32_e32 v202, v33, v159
	v_fmac_f32_e32 v203, v33, v175
	v_fmac_f32_e32 v200, v30, v128
	v_fmac_f32_e32 v201, v30, v144
	v_fmac_f32_e32 v202, v30, v160
	v_fmac_f32_e32 v203, v30, v180
	v_fmac_f32_e32 v200, v31, v129
	v_fmac_f32_e32 v201, v31, v145
	v_fmac_f32_e32 v202, v31, v161
	v_fmac_f32_e32 v203, v31, v181
	v_fmac_f32_e32 v200, v28, v130
	v_fmac_f32_e32 v201, v28, v146
	v_fmac_f32_e32 v202, v28, v162
	v_fmac_f32_e32 v203, v28, v182
	v_fmac_f32_e32 v200, v29, v131
	v_fmac_f32_e32 v201, v29, v147
	v_fmac_f32_e32 v202, v29, v163
	v_fmac_f32_e32 v203, v29, v183
	v_fmac_f32_e32 v200, v26, v132
	v_fmac_f32_e32 v201, v26, v148
	v_fmac_f32_e32 v202, v26, v164
	v_fmac_f32_e32 v203, v26, v184
	v_fmac_f32_e32 v200, v27, v133
	v_fmac_f32_e32 v201, v27, v149
	v_fmac_f32_e32 v202, v27, v165
	v_fmac_f32_e32 v203, v27, v185
	v_fmac_f32_e32 v200, v20, v134
	v_fmac_f32_e32 v201, v20, v150
	v_fmac_f32_e32 v202, v20, v166
	v_fmac_f32_e32 v203, v20, v186
	v_fmac_f32_e32 v200, v21, v135
	v_fmac_f32_e32 v201, v21, v151
	v_fmac_f32_e32 v202, v21, v167
	v_fmac_f32_e32 v203, v21, v187
	v_fmac_f32_e32 v200, v22, v136
	v_fmac_f32_e32 v201, v22, v152
	v_fmac_f32_e32 v202, v22, v168
	v_fmac_f32_e32 v203, v22, v188
	v_fmac_f32_e32 v200, v23, v137
	v_fmac_f32_e32 v201, v23, v153
	v_fmac_f32_e32 v202, v23, v169
	v_fmac_f32_e32 v203, v23, v189
	v_fmac_f32_e32 v200, v24, v138
	v_fmac_f32_e32 v201, v24, v154
	v_fmac_f32_e32 v202, v24, v170
	v_fmac_f32_e32 v203, v24, v190
	v_fmac_f32_e32 v200, v25, v139
	v_fmac_f32_e32 v201, v25, v155
	v_fmac_f32_e32 v202, v25, v171
	v_fmac_f32_e32 v203, v25, v191
	s_nop 1
	v_add_f32_dpp v192, v192, v192 quad_perm:[1,0,3,2] row_mask:0xf bank_mask:0xf
	v_add_f32_dpp v193, v193, v193 quad_perm:[1,0,3,2] row_mask:0xf bank_mask:0xf
	v_add_f32_dpp v194, v194, v194 quad_perm:[1,0,3,2] row_mask:0xf bank_mask:0xf
	v_add_f32_dpp v195, v195, v195 quad_perm:[1,0,3,2] row_mask:0xf bank_mask:0xf
	v_add_f32_dpp v196, v196, v196 quad_perm:[1,0,3,2] row_mask:0xf bank_mask:0xf
	v_add_f32_dpp v197, v197, v197 quad_perm:[1,0,3,2] row_mask:0xf bank_mask:0xf
	v_add_f32_dpp v198, v198, v198 quad_perm:[1,0,3,2] row_mask:0xf bank_mask:0xf
	v_add_f32_dpp v199, v199, v199 quad_perm:[1,0,3,2] row_mask:0xf bank_mask:0xf
	v_add_f32_dpp v200, v200, v200 quad_perm:[1,0,3,2] row_mask:0xf bank_mask:0xf
	v_add_f32_dpp v201, v201, v201 quad_perm:[1,0,3,2] row_mask:0xf bank_mask:0xf
	v_add_f32_dpp v202, v202, v202 quad_perm:[1,0,3,2] row_mask:0xf bank_mask:0xf
	v_add_f32_dpp v203, v203, v203 quad_perm:[1,0,3,2] row_mask:0xf bank_mask:0xf
	v_add_f32_dpp v192, v192, v192 quad_perm:[2,3,0,1] row_mask:0xf bank_mask:0xf
	v_add_f32_dpp v193, v193, v193 quad_perm:[2,3,0,1] row_mask:0xf bank_mask:0xf
	v_add_f32_dpp v194, v194, v194 quad_perm:[2,3,0,1] row_mask:0xf bank_mask:0xf
	v_add_f32_dpp v195, v195, v195 quad_perm:[2,3,0,1] row_mask:0xf bank_mask:0xf
	v_add_f32_dpp v196, v196, v196 quad_perm:[2,3,0,1] row_mask:0xf bank_mask:0xf
	v_add_f32_dpp v197, v197, v197 quad_perm:[2,3,0,1] row_mask:0xf bank_mask:0xf
	v_add_f32_dpp v198, v198, v198 quad_perm:[2,3,0,1] row_mask:0xf bank_mask:0xf
	v_add_f32_dpp v199, v199, v199 quad_perm:[2,3,0,1] row_mask:0xf bank_mask:0xf
	v_add_f32_dpp v200, v200, v200 quad_perm:[2,3,0,1] row_mask:0xf bank_mask:0xf
	v_add_f32_dpp v201, v201, v201 quad_perm:[2,3,0,1] row_mask:0xf bank_mask:0xf
	v_add_f32_dpp v202, v202, v202 quad_perm:[2,3,0,1] row_mask:0xf bank_mask:0xf
	v_add_f32_dpp v203, v203, v203 quad_perm:[2,3,0,1] row_mask:0xf bank_mask:0xf
	v_add_f32_dpp v192, v192, v192 row_half_mirror row_mask:0xf bank_mask:0xf
	v_add_f32_dpp v193, v193, v193 row_half_mirror row_mask:0xf bank_mask:0xf
	v_add_f32_dpp v194, v194, v194 row_half_mirror row_mask:0xf bank_mask:0xf
	v_add_f32_dpp v195, v195, v195 row_half_mirror row_mask:0xf bank_mask:0xf
	v_add_f32_dpp v196, v196, v196 row_half_mirror row_mask:0xf bank_mask:0xf
	v_add_f32_dpp v197, v197, v197 row_half_mirror row_mask:0xf bank_mask:0xf
	v_add_f32_dpp v198, v198, v198 row_half_mirror row_mask:0xf bank_mask:0xf
	v_add_f32_dpp v199, v199, v199 row_half_mirror row_mask:0xf bank_mask:0xf
	v_add_f32_dpp v200, v200, v200 row_half_mirror row_mask:0xf bank_mask:0xf
	v_add_f32_dpp v201, v201, v201 row_half_mirror row_mask:0xf bank_mask:0xf
	v_add_f32_dpp v202, v202, v202 row_half_mirror row_mask:0xf bank_mask:0xf
	v_add_f32_dpp v203, v203, v203 row_half_mirror row_mask:0xf bank_mask:0xf
	v_add_f32_dpp v192, v192, v192 row_mirror row_mask:0xf bank_mask:0xf
	v_add_f32_dpp v193, v193, v193 row_mirror row_mask:0xf bank_mask:0xf
	v_add_f32_dpp v194, v194, v194 row_mirror row_mask:0xf bank_mask:0xf
	v_add_f32_dpp v195, v195, v195 row_mirror row_mask:0xf bank_mask:0xf
	v_add_f32_dpp v196, v196, v196 row_mirror row_mask:0xf bank_mask:0xf
	v_add_f32_dpp v197, v197, v197 row_mirror row_mask:0xf bank_mask:0xf
	v_add_f32_dpp v198, v198, v198 row_mirror row_mask:0xf bank_mask:0xf
	v_add_f32_dpp v199, v199, v199 row_mirror row_mask:0xf bank_mask:0xf
	v_add_f32_dpp v200, v200, v200 row_mirror row_mask:0xf bank_mask:0xf
	v_add_f32_dpp v201, v201, v201 row_mirror row_mask:0xf bank_mask:0xf
	v_add_f32_dpp v202, v202, v202 row_mirror row_mask:0xf bank_mask:0xf
;     DEVI float* dt() const { return (float*)(ws + WS_DT); }
;     DEVI float* logf() const { return (float*)(ws + WS_LOGF); }
; DEVI float softplus_f(float x) { return x > 20.f ? x : log1pf(expf(x)); }
; template <int WHICH> DEVI void adaln_apply(const P& p, int l, int r, int lane_in, float (&v)[16]) {
;     ...
;             dot[jj] = wave_sum(a); }
;         if (lane < 8) {
;             float d = dot[0];
; #pragma unroll
;             for (int jj = 1; jj < 8; ++jj) d = (lane == jj) ? dot[jj] : d;
;             p.dt()[(size_t)r * 8 + lane] = softplus_f(d + dtb[lane]);
;         } else if (lane < 12) {
;             const int hd = lane - 8; float d = dot[8];
; #pragma unroll
;             for (int jj = 9; jj < 12; ++jj) d = (lane == jj) ? dot[jj] : d;
;             const float lf = -softplus_f(-(d + fb[hd]));
;             p.logf()[(size_t)r * 4 + hd] = lf;
;             if (r < M_P) p.out[OUT_LFP + ((size_t)l * M_P + r) * 4 + hd] = lf; else p.out[OUT_LFS + ((size_t)l * M_S + (r - M_P)) * 4 + hd] = lf;
;         }
	v_add_f32_dpp v203, v203, v203 row_mirror row_mask:0xf bank_mask:0xf
	v_add_f32_dpp v192, v192, v192 row_bcast:15 row_mask:0xa bank_mask:0xf
	v_add_f32_dpp v193, v193, v193 row_bcast:15 row_mask:0xa bank_mask:0xf
	v_add_f32_dpp v194, v194, v194 row_bcast:15 row_mask:0xa bank_mask:0xf
	v_add_f32_dpp v195, v195, v195 row_bcast:15 row_mask:0xa bank_mask:0xf
	v_add_f32_dpp v196, v196, v196 row_bcast:15 row_mask:0xa bank_mask:0xf
	v_add_f32_dpp v197, v197, v197 row_bcast:15 row_mask:0xa bank_mask:0xf
	v_add_f32_dpp v198, v198, v198 row_bcast:15 row_mask:0xa bank_mask:0xf
	v_add_f32_dpp v199, v199, v199 row_bcast:15 row_mask:0xa bank_mask:0xf
	v_add_f32_dpp v200, v200, v200 row_bcast:15 row_mask:0xa bank_mask:0xf
	v_add_f32_dpp v201, v201, v201 row_bcast:15 row_mask:0xa bank_mask:0xf
	v_add_f32_dpp v202, v202, v202 row_bcast:15 row_mask:0xa bank_mask:0xf
	v_add_f32_dpp v203, v203, v203 row_bcast:15 row_mask:0xa bank_mask:0xf
	v_add_f32_dpp v192, v192, v192 row_bcast:31 row_mask:0xc bank_mask:0xf
	v_add_f32_dpp v193, v193, v193 row_bcast:31 row_mask:0xc bank_mask:0xf
	v_add_f32_dpp v194, v194, v194 row_bcast:31 row_mask:0xc bank_mask:0xf
	v_add_f32_dpp v195, v195, v195 row_bcast:31 row_mask:0xc bank_mask:0xf
	v_add_f32_dpp v196, v196, v196 row_bcast:31 row_mask:0xc bank_mask:0xf
	v_add_f32_dpp v197, v197, v197 row_bcast:31 row_mask:0xc bank_mask:0xf
	v_add_f32_dpp v198, v198, v198 row_bcast:31 row_mask:0xc bank_mask:0xf
	v_add_f32_dpp v199, v199, v199 row_bcast:31 row_mask:0xc bank_mask:0xf
	v_add_f32_dpp v200, v200, v200 row_bcast:31 row_mask:0xc bank_mask:0xf
	v_add_f32_dpp v201, v201, v201 row_bcast:31 row_mask:0xc bank_mask:0xf
	v_add_f32_dpp v202, v202, v202 row_bcast:31 row_mask:0xc bank_mask:0xf
	v_add_f32_dpp v203, v203, v203 row_bcast:31 row_mask:0xc bank_mask:0xf
	s_nop 1
	v_readlane_b32 s18, v192, 63
	v_readlane_b32 s19, v193, 63
	v_readlane_b32 s20, v194, 63
	v_readlane_b32 s21, v195, 63
	v_readlane_b32 s22, v196, 63
	v_readlane_b32 s23, v197, 63
	s_nop 1
	v_writelane_b32 v216, s18, 0
	v_writelane_b32 v216, s19, 1
	v_writelane_b32 v216, s20, 2
	v_writelane_b32 v216, s21, 3
	v_writelane_b32 v216, s22, 4
	v_writelane_b32 v216, s23, 5
	v_readlane_b32 s18, v198, 63
	v_readlane_b32 s19, v199, 63
	v_readlane_b32 s20, v200, 63
	v_readlane_b32 s21, v201, 63
	v_readlane_b32 s22, v202, 63
	v_readlane_b32 s23, v203, 63
	s_nop 1
	v_writelane_b32 v216, s18, 6
	v_writelane_b32 v216, s19, 7
	v_writelane_b32 v216, s20, 8
	v_writelane_b32 v216, s21, 9
	v_writelane_b32 v216, s22, 10
	v_writelane_b32 v216, s23, 11
	v_mov_b32_e32 v46, v216
	v_mov_b32_e32 v35, v216
	v_mov_b32_e32 v37, v216
	v_mov_b32_e32 v39, v216
	v_mov_b32_e32 v41, v216
	v_mov_b32_e32 v43, v216
	v_mov_b32_e32 v19, v216
	v_mov_b32_e32 v45, v216
	v_mov_b32_e32 v48, v216
	v_mov_b32_e32 v20, v216
	v_mov_b32_e32 v22, v216
	v_mov_b32_e32 v24, v216
	v_mov_b32_e32 v34, v217
	v_mov_b32_e32 v36, v217
	v_mov_b32_e32 v38, v217
	v_mov_b32_e32 v40, v217
	v_mov_b32_e32 v42, v217
	v_mov_b32_e32 v18, v217
	v_mov_b32_e32 v44, v217
	v_mov_b32_e32 v47, v217
	v_mov_b32_e32 v49, v217
	v_mov_b32_e32 v21, v217
	v_mov_b32_e32 v23, v217
	v_mov_b32_e32 v25, v217
	s_load_dwordx2 s[18:19], s[0:1], 0x80
	s_load_dwordx2 s[20:21], s[0:1], 0xb0
	s_waitcnt lgkmcnt(0)
	v_cmp_lt_i32_e32 vcc, 7, v68
	s_nop 3
	s_and_saveexec_b64 s[22:23], vcc
	s_xor_b64 s[22:23], exec, s[22:23]
	s_cbranch_execz .LBB0_115
	v_cmp_gt_u32_e32 vcc, 12, v68
	s_and_saveexec_b64 s[24:25], vcc
	s_cbranch_execz .LBB0_114
	v_lshl_add_u64 v[18:19], s[20:21], 0, v[62:63]
	v_add_u32_e32 v66, -8, v68
	v_lshl_add_u64 v[18:19], v[66:67], 2, v[18:19]
	global_load_dword v18, v[18:19], off
	v_add_f32_e32 v19, v48, v49
	s_waitcnt lgkmcnt(2)
	v_add_f32_e32 v20, v20, v21
	v_cmp_eq_u32_e32 vcc, 9, v68
	s_waitcnt lgkmcnt(1)
	v_add_f32_e32 v21, v22, v23
	s_waitcnt lgkmcnt(0)
	v_add_f32_e32 v22, v24, v25
	v_cndmask_b32_e32 v19, v19, v20, vcc
	v_cmp_eq_u32_e32 vcc, 10, v68
	s_mov_b32 s15, 0xc1a00000
	s_nop 0
	v_cndmask_b32_e32 v19, v19, v21, vcc
	v_cmp_eq_u32_e32 vcc, 11, v68
	s_nop 1
	v_cndmask_b32_e32 v19, v19, v22, vcc
	s_waitcnt vmcnt(0)
	v_add_f32_e32 v18, v19, v18
	v_xor_b32_e32 v19, 0x80000000, v18
	v_cmp_ngt_f32_e32 vcc, s15, v18
	s_and_saveexec_b64 s[20:21], vcc
	s_cbranch_execz .LBB0_110
;     DEVI float* logf() const { return (float*)(ws + WS_LOGF); }
; DEVI float silu_f(float x) { return x / (1.f + expf(-x)); }
; DEVI float softplus_f(float x) { return x > 20.f ? x : log1pf(expf(x)); }
; template <int WHICH> DEVI void adaln_apply(const P& p, int l, int r, int lane_in, float (&v)[16]) {
;     ...
;         } else if (lane < 12) {
;             const int hd = lane - 8; float d = dot[8];
; #pragma unroll
;             for (int jj = 9; jj < 12; ++jj) d = (lane == jj) ? dot[jj] : d;
;             const float lf = -softplus_f(-(d + fb[hd]));
;             p.logf()[(size_t)r * 4 + hd] = lf;
	v_mul_f32_e32 v19, 0xbfb8aa3b, v18
	v_rndne_f32_e32 v20, v19
	s_mov_b32 s15, 0xbfb8aa3b
	v_sub_f32_e32 v21, v19, v20
	v_fma_f32 v19, v18, s15, -v19
	v_fmac_f32_e32 v19, 0xb2a5705f, v18
	v_add_f32_e32 v19, v21, v19
	v_cvt_i32_f32_e32 v20, v20
	v_exp_f32_e32 v19, v19
	s_mov_b32 s15, 0x42ce8ed0
	v_cmp_nlt_f32_e32 vcc, s15, v18
	s_mov_b32 s15, 0xc2b17218
	v_ldexp_f32 v19, v19, v20
	v_cndmask_b32_e32 v19, 0, v19, vcc
	v_cmp_ngt_f32_e32 vcc, s15, v18
	s_mov_b32 s15, 0x3f2aaaab
	s_nop 0
	v_cndmask_b32_e32 v32, v215, v19, vcc
	v_add_f32_e32 v20, 1.0, v32
	v_add_f32_e32 v18, -1.0, v20
	v_sub_f32_e32 v19, v18, v20
	v_add_f32_e32 v19, 1.0, v19
	v_sub_f32_e32 v18, v32, v18
	v_add_f32_e32 v21, v18, v19
	v_frexp_mant_f32_e32 v22, v20
	v_cvt_f64_f32_e32 v[18:19], v20
	v_frexp_exp_i32_f64_e32 v18, v[18:19]
	v_cmp_gt_f32_e32 vcc, s15, v22
	s_mov_b32 s15, 0x3f317218
	s_nop 0
	v_subbrev_co_u32_e32 v26, vcc, 0, v18, vcc
	v_sub_u32_e32 v18, 0, v26
	v_ldexp_f32 v19, v20, v18
	v_add_f32_e32 v20, -1.0, v19
	v_add_f32_e32 v22, 1.0, v19
	v_ldexp_f32 v18, v21, v18
	v_add_f32_e32 v21, 1.0, v20
	v_add_f32_e32 v23, -1.0, v22
	v_sub_f32_e32 v21, v19, v21
	v_sub_f32_e32 v19, v19, v23
	v_add_f32_e32 v21, v18, v21
	v_add_f32_e32 v18, v18, v19
	v_add_f32_e32 v27, v22, v18
	v_rcp_f32_e32 v29, v27
	v_sub_f32_e32 v19, v22, v27
	v_add_f32_e32 v28, v18, v19
	v_add_f32_e32 v19, v20, v21
	v_mul_f32_e32 v31, v19, v29
	v_sub_f32_e32 v18, v20, v19
	v_mul_f32_e32 v20, v27, v31
	v_fma_f32 v22, v31, v27, -v20
	v_fmac_f32_e32 v22, v31, v28
	v_add_f32_e32 v30, v21, v18
	v_add_f32_e32 v18, v20, v22
	v_sub_f32_e32 v21, v19, v18
	v_pk_add_f32 v[24:25], v[18:19], v[20:21] neg_lo:[0,1] neg_hi:[0,1]
	v_mov_b32_e32 v23, v18
	v_pk_add_f32 v[18:19], v[24:25], v[22:23] neg_lo:[0,1] neg_hi:[0,1]
	s_nop 0
	v_add_f32_e32 v19, v30, v19
	v_add_f32_e32 v18, v18, v19
	v_add_f32_e32 v19, v21, v18
	v_mul_f32_e32 v30, v29, v19
	v_mul_f32_e32 v20, v27, v30
	v_fma_f32 v22, v30, v27, -v20
	v_fmac_f32_e32 v22, v30, v28
	v_sub_f32_e32 v21, v21, v19
	v_add_f32_e32 v27, v18, v21
	v_add_f32_e32 v18, v20, v22
	v_sub_f32_e32 v21, v19, v18
	v_pk_add_f32 v[24:25], v[18:19], v[20:21] neg_lo:[0,1] neg_hi:[0,1]
	v_mov_b32_e32 v23, v18
	v_pk_add_f32 v[18:19], v[24:25], v[22:23] neg_lo:[0,1] neg_hi:[0,1]
	s_nop 0
	v_add_f32_e32 v19, v27, v19
	v_add_f32_e32 v18, v18, v19
	v_add_f32_e32 v19, v31, v30
	v_add_f32_e32 v18, v21, v18
	v_sub_f32_e32 v20, v19, v31
	v_mul_f32_e32 v18, v29, v18
	v_sub_f32_e32 v20, v30, v20
	v_add_f32_e32 v20, v20, v18
	v_add_f32_e32 v22, v19, v20
	v_mul_f32_e32 v23, v22, v22
	v_fmamk_f32 v18, v23, 0x3e9b6dac, v212
	v_fmaak_f32 v177, v23, v18, 0x3f2aaada
	v_cvt_f32_i32_e32 v18, v26
	v_sub_f32_e32 v19, v22, v19
	v_sub_f32_e32 v19, v20, v19
	v_ldexp_f32 v24, v19, 1
	v_mul_f32_e32 v19, v22, v23
	v_ldexp_f32 v21, v22, 1
	v_pk_mul_f32 v[22:23], v[18:19], v[176:177]
	s_nop 0
	v_fma_f32 v20, v18, s15, -v22
	v_fmac_f32_e32 v20, 0xb102e308, v18
	v_pk_add_f32 v[18:19], v[22:23], v[20:21]
	s_mov_b32 s15, 0x7f800000
	v_sub_f32_e32 v21, v19, v21
	v_sub_f32_e32 v21, v23, v21
	v_add_f32_e32 v25, v24, v21
	v_mov_b32_e32 v24, v22
	v_pk_add_f32 v[22:23], v[18:19], v[22:23] neg_lo:[0,1] neg_hi:[0,1]
	v_pk_add_f32 v[26:27], v[18:19], v[24:25]
	v_mov_b32_e32 v21, v18
	v_mov_b32_e32 v23, v27
	v_pk_add_f32 v[28:29], v[20:21], v[22:23] neg_lo:[0,1] neg_hi:[0,1]
	v_pk_add_f32 v[20:21], v[20:21], v[22:23]
	v_mov_b32_e32 v24, v25
	v_pk_add_f32 v[22:23], v[20:21], v[18:19] op_sel:[1,0] op_sel_hi:[0,1] neg_lo:[0,1] neg_hi:[0,1]
	v_pk_add_f32 v[30:31], v[26:27], v[22:23] op_sel_hi:[1,0] neg_lo:[0,1] neg_hi:[0,1]
	v_mov_b32_e32 v26, v27
	v_mov_b32_e32 v27, v21
	v_pk_mov_b32 v[22:23], v[18:19], v[22:23] op_sel:[1,0]
	v_mov_b32_e32 v25, v18
	v_pk_add_f32 v[22:23], v[26:27], v[22:23] neg_lo:[0,1] neg_hi:[0,1]
	v_mov_b32_e32 v30, v28
	v_pk_add_f32 v[18:19], v[24:25], v[22:23] neg_lo:[0,1] neg_hi:[0,1]
	v_mov_b32_e32 v29, v21
	v_pk_add_f32 v[22:23], v[30:31], v[18:19]
	v_cmp_neq_f32_e32 vcc, s15, v32
	v_pk_add_f32 v[24:25], v[22:23], v[22:23] op_sel:[0,1] op_sel_hi:[1,0]
	s_mov_b32 s15, 0x33800000
	v_pk_add_f32 v[20:21], v[20:21], v[24:25] op_sel:[1,0] op_sel_hi:[0,1]
	v_mov_b32_e32 v23, v20
	v_pk_add_f32 v[26:27], v[22:23], v[28:29] neg_lo:[0,1] neg_hi:[0,1]
	v_mov_b32_e32 v19, v24
	v_sub_f32_e32 v21, v22, v26
	v_pk_add_f32 v[18:19], v[18:19], v[26:27] neg_lo:[0,1] neg_hi:[0,1]
	v_sub_f32_e32 v21, v28, v21
	v_add_f32_e32 v18, v18, v21
	v_add_f32_e32 v18, v18, v19
	v_add_f32_e32 v18, v20, v18
	v_cndmask_b32_e32 v18, v215, v18, vcc
	v_cmp_lt_f32_e64 vcc, |v32|, s15
	s_nop 1
	v_cndmask_b32_e32 v19, v18, v32, vcc

;     ...
;     for (int j0 = 0; j0 < NTL * 16; j0 += 16) {
;         u32x4_t w[16]; float cj[16];
; #pragma unroll
;         for (int jj = 0; jj < 16; ++jj) { const u32x2_t pr = pl[j0 + jj]; const int ej = __builtin_amdgcn_readfirstlane((int)pr.x); cj[jj] = __uint_as_float(pr.y);
;             w[jj] = *(const u32x4_t*)(v8 + (size_t)ej * D + 16 * lane); }
; #pragma unroll
;         for (int jj = 0; jj < 16; ++jj) { const float c = cj[jj];
; #pragma unroll
;             for (int q = 0; q < 4; ++q) { const f32x2_t lo = __builtin_amdgcn_cvt_pk_f32_fp8((int)w[jj][q], false), hi = __builtin_amdgcn_cvt_pk_f32_fp8((int)w[jj][q], true);
;                 o[4 * q] += c * lo[0]; o[4 * q + 1] += c * lo[1]; o[4 * q + 2] += c * hi[0]; o[4 * q + 3] += c * hi[1]; } }
;     }
.Lg2_nobar:
	s_and_b32 s9, s22, 7
	s_lshr_b32 s10, s22, 3
	s_mul_i32 s11, s9, s20
	s_lshl_b32 s23, s10, 9
	s_add_u32 s14, s58, s11
	s_addc_u32 s15, s59, 0
	s_add_u32 s14, s14, s23
	s_addc_u32 s15, s15, 0
	s_mul_i32 s11, s9, s34
	s_add_u32 s11, s11, s48
	s_lshr_b32 s11, s11, 13
	s_mul_i32 s11, s11, 0x6000
	s_add_u32 s16, s60, s11
	s_addc_u32 s17, s61, 0
	s_add_u32 s16, s16, s23
	s_addc_u32 s17, s17, 0
	global_load_dwordx2 v[58:59], v6, s[14:15]
	global_load_dwordx2 v[60:61], v6, s[16:17]
	s_lshl_b32 s9, s9, 10
	v_add_u32_e32 v7, s9, v5
	s_add_u32 s10, s22, 1
	s_and_b32 s9, s10, 7
	s_lshl_b32 s9, s9, 10
	v_add_u32_e32 v8, s9, v5
	s_lshr_b32 s10, s10, 3
	s_lshl_b32 s10, s10, 7
	s_add_u32 s12, s56, s10
	s_addc_u32 s13, s57, 0
	ds_read_b128 v[84:87], v7 offset:0
	ds_read_b128 v[88:91], v7 offset:16
	ds_read_b128 v[92:95], v7 offset:32
	ds_read_b128 v[96:99], v7 offset:48
	ds_read_b128 v[104:107], v7 offset:64
	ds_read_b128 v[108:111], v7 offset:80
	ds_read_b128 v[112:115], v7 offset:96
	ds_read_b128 v[180:183], v7 offset:112
	ds_read_b128 v[26:29], v8 offset:0
	ds_read_b128 v[30:33], v8 offset:16
	ds_read_b128 v[34:37], v8 offset:32
	ds_read_b128 v[38:41], v8 offset:48
	ds_read_b128 v[42:45], v8 offset:64
	ds_read_b128 v[46:49], v8 offset:80
	ds_read_b128 v[50:53], v8 offset:96
	ds_read_b128 v[54:57], v8 offset:112
	s_waitcnt lgkmcnt(0)
	v_lshl_add_u32 v68, v26, 10, v4
	v_lshl_add_u32 v69, v28, 10, v4
	v_lshl_add_u32 v70, v30, 10, v4
	v_lshl_add_u32 v71, v32, 10, v4
	v_lshl_add_u32 v72, v34, 10, v4
	v_lshl_add_u32 v73, v36, 10, v4
	v_lshl_add_u32 v74, v38, 10, v4
	v_lshl_add_u32 v75, v40, 10, v4
	v_lshl_add_u32 v76, v42, 10, v4
	v_lshl_add_u32 v77, v44, 10, v4
	v_lshl_add_u32 v78, v46, 10, v4
	v_lshl_add_u32 v79, v48, 10, v4
	v_lshl_add_u32 v80, v50, 10, v4
	v_lshl_add_u32 v81, v52, 10, v4
	v_lshl_add_u32 v82, v54, 10, v4
	v_lshl_add_u32 v83, v56, 10, v4
	s_waitcnt vmcnt(16)
	v_cvt_pk_f32_fp8_e32 v[26:27], v120
	v_cvt_pk_f32_fp8_sdwa v[28:29], v120 src0_sel:WORD_1
	v_cvt_pk_f32_fp8_e32 v[30:31], v121
	v_cvt_pk_f32_fp8_sdwa v[32:33], v121 src0_sel:WORD_1
	v_cvt_pk_f32_fp8_e32 v[34:35], v122
	v_cvt_pk_f32_fp8_sdwa v[36:37], v122 src0_sel:WORD_1
	v_cvt_pk_f32_fp8_e32 v[38:39], v123
	v_cvt_pk_f32_fp8_sdwa v[40:41], v123 src0_sel:WORD_1
	v_cvt_pk_f32_fp8_e32 v[42:43], v124
	v_cvt_pk_f32_fp8_sdwa v[44:45], v124 src0_sel:WORD_1
	v_cvt_pk_f32_fp8_e32 v[46:47], v125
	v_cvt_pk_f32_fp8_sdwa v[48:49], v125 src0_sel:WORD_1
	v_cvt_pk_f32_fp8_e32 v[50:51], v126
	v_cvt_pk_f32_fp8_sdwa v[52:53], v126 src0_sel:WORD_1
	v_cvt_pk_f32_fp8_e32 v[54:55], v127
	v_cvt_pk_f32_fp8_sdwa v[56:57], v127 src0_sel:WORD_1
	global_load_dwordx4 v[120:123], v68, s[12:13]
	global_load_dwordx4 v[124:127], v69, s[12:13]
	v_pk_mul_f32 v[10:11], v[84:85], v[26:27] op_sel:[1,0]
	v_pk_mul_f32 v[12:13], v[84:85], v[28:29] op_sel:[1,0]
	v_pk_mul_f32 v[14:15], v[84:85], v[30:31] op_sel:[1,0]
	v_pk_mul_f32 v[16:17], v[84:85], v[32:33] op_sel:[1,0]
	v_pk_mul_f32 v[18:19], v[84:85], v[34:35] op_sel:[1,0]
	v_pk_mul_f32 v[20:21], v[84:85], v[36:37] op_sel:[1,0]
	v_pk_mul_f32 v[22:23], v[84:85], v[38:39] op_sel:[1,0]
	v_pk_mul_f32 v[24:25], v[84:85], v[40:41] op_sel:[1,0]
	v_pk_fma_f32 v[10:11], v[86:87], v[42:43], v[10:11] op_sel:[1,0,0]
	v_pk_fma_f32 v[12:13], v[86:87], v[44:45], v[12:13] op_sel:[1,0,0]
	v_pk_fma_f32 v[14:15], v[86:87], v[46:47], v[14:15] op_sel:[1,0,0]
	v_pk_fma_f32 v[16:17], v[86:87], v[48:49], v[16:17] op_sel:[1,0,0]
	v_pk_fma_f32 v[18:19], v[86:87], v[50:51], v[18:19] op_sel:[1,0,0]
	v_pk_fma_f32 v[20:21], v[86:87], v[52:53], v[20:21] op_sel:[1,0,0]
	v_pk_fma_f32 v[22:23], v[86:87], v[54:55], v[22:23] op_sel:[1,0,0]
	v_pk_fma_f32 v[24:25], v[86:87], v[56:57], v[24:25] op_sel:[1,0,0]
	s_waitcnt vmcnt(16)
	v_cvt_pk_f32_fp8_e32 v[26:27], v128
	v_cvt_pk_f32_fp8_sdwa v[28:29], v128 src0_sel:WORD_1
	v_cvt_pk_f32_fp8_e32 v[30:31], v129
	v_cvt_pk_f32_fp8_sdwa v[32:33], v129 src0_sel:WORD_1
	v_cvt_pk_f32_fp8_e32 v[34:35], v130
	v_cvt_pk_f32_fp8_sdwa v[36:37], v130 src0_sel:WORD_1
	v_cvt_pk_f32_fp8_e32 v[38:39], v131
	v_cvt_pk_f32_fp8_sdwa v[40:41], v131 src0_sel:WORD_1
	v_cvt_pk_f32_fp8_e32 v[42:43], v132
	v_cvt_pk_f32_fp8_sdwa v[44:45], v132 src0_sel:WORD_1
	v_cvt_pk_f32_fp8_e32 v[46:47], v133
	v_cvt_pk_f32_fp8_sdwa v[48:49], v133 src0_sel:WORD_1
	v_cvt_pk_f32_fp8_e32 v[50:51], v134
	v_cvt_pk_f32_fp8_sdwa v[52:53], v134 src0_sel:WORD_1
	v_cvt_pk_f32_fp8_e32 v[54:55], v135
	v_cvt_pk_f32_fp8_sdwa v[56:57], v135 src0_sel:WORD_1
	global_load_dwordx4 v[128:131], v70, s[12:13]
	global_load_dwordx4 v[132:135], v71, s[12:13]
	v_pk_fma_f32 v[10:11], v[88:89], v[26:27], v[10:11] op_sel:[1,0,0]
	v_pk_fma_f32 v[12:13], v[88:89], v[28:29], v[12:13] op_sel:[1,0,0]
	v_pk_fma_f32 v[14:15], v[88:89], v[30:31], v[14:15] op_sel:[1,0,0]
	v_pk_fma_f32 v[16:17], v[88:89], v[32:33], v[16:17] op_sel:[1,0,0]
	v_pk_fma_f32 v[18:19], v[88:89], v[34:35], v[18:19] op_sel:[1,0,0]
	v_pk_fma_f32 v[20:21], v[88:89], v[36:37], v[20:21] op_sel:[1,0,0]
	v_pk_fma_f32 v[22:23], v[88:89], v[38:39], v[22:23] op_sel:[1,0,0]
	v_pk_fma_f32 v[24:25], v[88:89], v[40:41], v[24:25] op_sel:[1,0,0]
	v_pk_fma_f32 v[10:11], v[90:91], v[42:43], v[10:11] op_sel:[1,0,0]
	v_pk_fma_f32 v[12:13], v[90:91], v[44:45], v[12:13] op_sel:[1,0,0]
	v_pk_fma_f32 v[14:15], v[90:91], v[46:47], v[14:15] op_sel:[1,0,0]
	v_pk_fma_f32 v[16:17], v[90:91], v[48:49], v[16:17] op_sel:[1,0,0]
	v_pk_fma_f32 v[18:19], v[90:91], v[50:51], v[18:19] op_sel:[1,0,0]
	v_pk_fma_f32 v[20:21], v[90:91], v[52:53], v[20:21] op_sel:[1,0,0]
	v_pk_fma_f32 v[22:23], v[90:91], v[54:55], v[22:23] op_sel:[1,0,0]
	v_pk_fma_f32 v[24:25], v[90:91], v[56:57], v[24:25] op_sel:[1,0,0]
	s_waitcnt vmcnt(16)
;     ...
;         for (int jj = 0; jj < 16; ++jj) { const float c = cj[jj];
; #pragma unroll
;             for (int q = 0; q < 4; ++q) { const f32x2_t lo = __builtin_amdgcn_cvt_pk_f32_fp8((int)w[jj][q], false), hi = __builtin_amdgcn_cvt_pk_f32_fp8((int)w[jj][q], true);
;                 o[4 * q] += c * lo[0]; o[4 * q + 1] += c * lo[1]; o[4 * q + 2] += c * hi[0]; o[4 * q + 3] += c * hi[1]; } }
	v_cvt_pk_f32_fp8_e32 v[26:27], v136
	v_cvt_pk_f32_fp8_sdwa v[28:29], v136 src0_sel:WORD_1
	v_cvt_pk_f32_fp8_e32 v[30:31], v137
	v_cvt_pk_f32_fp8_sdwa v[32:33], v137 src0_sel:WORD_1
	v_cvt_pk_f32_fp8_e32 v[34:35], v138
	v_cvt_pk_f32_fp8_sdwa v[36:37], v138 src0_sel:WORD_1
	v_cvt_pk_f32_fp8_e32 v[38:39], v139
	v_cvt_pk_f32_fp8_sdwa v[40:41], v139 src0_sel:WORD_1
	v_cvt_pk_f32_fp8_e32 v[42:43], v140
	v_cvt_pk_f32_fp8_sdwa v[44:45], v140 src0_sel:WORD_1
	v_cvt_pk_f32_fp8_e32 v[46:47], v141
	v_cvt_pk_f32_fp8_sdwa v[48:49], v141 src0_sel:WORD_1
	v_cvt_pk_f32_fp8_e32 v[50:51], v142
	v_cvt_pk_f32_fp8_sdwa v[52:53], v142 src0_sel:WORD_1
	v_cvt_pk_f32_fp8_e32 v[54:55], v143
	v_cvt_pk_f32_fp8_sdwa v[56:57], v143 src0_sel:WORD_1
	global_load_dwordx4 v[136:139], v72, s[12:13]
	global_load_dwordx4 v[140:143], v73, s[12:13]
	v_pk_fma_f32 v[10:11], v[92:93], v[26:27], v[10:11] op_sel:[1,0,0]
	v_pk_fma_f32 v[12:13], v[92:93], v[28:29], v[12:13] op_sel:[1,0,0]
	v_pk_fma_f32 v[14:15], v[92:93], v[30:31], v[14:15] op_sel:[1,0,0]
	v_pk_fma_f32 v[16:17], v[92:93], v[32:33], v[16:17] op_sel:[1,0,0]
	v_pk_fma_f32 v[18:19], v[92:93], v[34:35], v[18:19] op_sel:[1,0,0]
	v_pk_fma_f32 v[20:21], v[92:93], v[36:37], v[20:21] op_sel:[1,0,0]
	v_pk_fma_f32 v[22:23], v[92:93], v[38:39], v[22:23] op_sel:[1,0,0]
	v_pk_fma_f32 v[24:25], v[92:93], v[40:41], v[24:25] op_sel:[1,0,0]
	v_pk_fma_f32 v[10:11], v[94:95], v[42:43], v[10:11] op_sel:[1,0,0]
	v_pk_fma_f32 v[12:13], v[94:95], v[44:45], v[12:13] op_sel:[1,0,0]
	v_pk_fma_f32 v[14:15], v[94:95], v[46:47], v[14:15] op_sel:[1,0,0]
	v_pk_fma_f32 v[16:17], v[94:95], v[48:49], v[16:17] op_sel:[1,0,0]
	v_pk_fma_f32 v[18:19], v[94:95], v[50:51], v[18:19] op_sel:[1,0,0]
	v_pk_fma_f32 v[20:21], v[94:95], v[52:53], v[20:21] op_sel:[1,0,0]
	v_pk_fma_f32 v[22:23], v[94:95], v[54:55], v[22:23] op_sel:[1,0,0]
	v_pk_fma_f32 v[24:25], v[94:95], v[56:57], v[24:25] op_sel:[1,0,0]
	s_waitcnt vmcnt(16)
	v_cvt_pk_f32_fp8_e32 v[26:27], v144
	v_cvt_pk_f32_fp8_sdwa v[28:29], v144 src0_sel:WORD_1
	v_cvt_pk_f32_fp8_e32 v[30:31], v145
	v_cvt_pk_f32_fp8_sdwa v[32:33], v145 src0_sel:WORD_1
	v_cvt_pk_f32_fp8_e32 v[34:35], v146
	v_cvt_pk_f32_fp8_sdwa v[36:37], v146 src0_sel:WORD_1
	v_cvt_pk_f32_fp8_e32 v[38:39], v147
	v_cvt_pk_f32_fp8_sdwa v[40:41], v147 src0_sel:WORD_1
	v_cvt_pk_f32_fp8_e32 v[42:43], v148
	v_cvt_pk_f32_fp8_sdwa v[44:45], v148 src0_sel:WORD_1
	v_cvt_pk_f32_fp8_e32 v[46:47], v149
	v_cvt_pk_f32_fp8_sdwa v[48:49], v149 src0_sel:WORD_1
	v_cvt_pk_f32_fp8_e32 v[50:51], v150
	v_cvt_pk_f32_fp8_sdwa v[52:53], v150 src0_sel:WORD_1
	v_cvt_pk_f32_fp8_e32 v[54:55], v151
	v_cvt_pk_f32_fp8_sdwa v[56:57], v151 src0_sel:WORD_1
	global_load_dwordx4 v[144:147], v74, s[12:13]
	global_load_dwordx4 v[148:151], v75, s[12:13]
	v_pk_fma_f32 v[10:11], v[96:97], v[26:27], v[10:11] op_sel:[1,0,0]
	v_pk_fma_f32 v[12:13], v[96:97], v[28:29], v[12:13] op_sel:[1,0,0]
	v_pk_fma_f32 v[14:15], v[96:97], v[30:31], v[14:15] op_sel:[1,0,0]
	v_pk_fma_f32 v[16:17], v[96:97], v[32:33], v[16:17] op_sel:[1,0,0]
	v_pk_fma_f32 v[18:19], v[96:97], v[34:35], v[18:19] op_sel:[1,0,0]
	v_pk_fma_f32 v[20:21], v[96:97], v[36:37], v[20:21] op_sel:[1,0,0]
	v_pk_fma_f32 v[22:23], v[96:97], v[38:39], v[22:23] op_sel:[1,0,0]
	v_pk_fma_f32 v[24:25], v[96:97], v[40:41], v[24:25] op_sel:[1,0,0]
	v_pk_fma_f32 v[10:11], v[98:99], v[42:43], v[10:11] op_sel:[1,0,0]
	v_pk_fma_f32 v[12:13], v[98:99], v[44:45], v[12:13] op_sel:[1,0,0]
	v_pk_fma_f32 v[14:15], v[98:99], v[46:47], v[14:15] op_sel:[1,0,0]
	v_pk_fma_f32 v[16:17], v[98:99], v[48:49], v[16:17] op_sel:[1,0,0]
	v_pk_fma_f32 v[18:19], v[98:99], v[50:51], v[18:19] op_sel:[1,0,0]
	v_pk_fma_f32 v[20:21], v[98:99], v[52:53], v[20:21] op_sel:[1,0,0]
	v_pk_fma_f32 v[22:23], v[98:99], v[54:55], v[22:23] op_sel:[1,0,0]
	v_pk_fma_f32 v[24:25], v[98:99], v[56:57], v[24:25] op_sel:[1,0,0]
	s_waitcnt vmcnt(16)
	v_cvt_pk_f32_fp8_e32 v[26:27], v152
	v_cvt_pk_f32_fp8_sdwa v[28:29], v152 src0_sel:WORD_1
	v_cvt_pk_f32_fp8_e32 v[30:31], v153
	v_cvt_pk_f32_fp8_sdwa v[32:33], v153 src0_sel:WORD_1
	v_cvt_pk_f32_fp8_e32 v[34:35], v154
	v_cvt_pk_f32_fp8_sdwa v[36:37], v154 src0_sel:WORD_1
	v_cvt_pk_f32_fp8_e32 v[38:39], v155
	v_cvt_pk_f32_fp8_sdwa v[40:41], v155 src0_sel:WORD_1
	v_cvt_pk_f32_fp8_e32 v[42:43], v156
	v_cvt_pk_f32_fp8_sdwa v[44:45], v156 src0_sel:WORD_1
	v_cvt_pk_f32_fp8_e32 v[46:47], v157
	v_cvt_pk_f32_fp8_sdwa v[48:49], v157 src0_sel:WORD_1
	v_cvt_pk_f32_fp8_e32 v[50:51], v158
	v_cvt_pk_f32_fp8_sdwa v[52:53], v158 src0_sel:WORD_1
	v_cvt_pk_f32_fp8_e32 v[54:55], v159
	v_cvt_pk_f32_fp8_sdwa v[56:57], v159 src0_sel:WORD_1
	global_load_dwordx4 v[152:155], v76, s[12:13]
	global_load_dwordx4 v[156:159], v77, s[12:13]
	v_pk_fma_f32 v[10:11], v[104:105], v[26:27], v[10:11] op_sel:[1,0,0]
	v_pk_fma_f32 v[12:13], v[104:105], v[28:29], v[12:13] op_sel:[1,0,0]
	v_pk_fma_f32 v[14:15], v[104:105], v[30:31], v[14:15] op_sel:[1,0,0]
	v_pk_fma_f32 v[16:17], v[104:105], v[32:33], v[16:17] op_sel:[1,0,0]
	v_pk_fma_f32 v[18:19], v[104:105], v[34:35], v[18:19] op_sel:[1,0,0]
	v_pk_fma_f32 v[20:21], v[104:105], v[36:37], v[20:21] op_sel:[1,0,0]
	v_pk_fma_f32 v[22:23], v[104:105], v[38:39], v[22:23] op_sel:[1,0,0]
	v_pk_fma_f32 v[24:25], v[104:105], v[40:41], v[24:25] op_sel:[1,0,0]
	v_pk_fma_f32 v[10:11], v[106:107], v[42:43], v[10:11] op_sel:[1,0,0]
	v_pk_fma_f32 v[12:13], v[106:107], v[44:45], v[12:13] op_sel:[1,0,0]
	v_pk_fma_f32 v[14:15], v[106:107], v[46:47], v[14:15] op_sel:[1,0,0]
	v_pk_fma_f32 v[16:17], v[106:107], v[48:49], v[16:17] op_sel:[1,0,0]
	v_pk_fma_f32 v[18:19], v[106:107], v[50:51], v[18:19] op_sel:[1,0,0]
	v_pk_fma_f32 v[20:21], v[106:107], v[52:53], v[20:21] op_sel:[1,0,0]
	v_pk_fma_f32 v[22:23], v[106:107], v[54:55], v[22:23] op_sel:[1,0,0]
	v_pk_fma_f32 v[24:25], v[106:107], v[56:57], v[24:25] op_sel:[1,0,0]
	s_waitcnt vmcnt(16)
;     ...
;     for (int j0 = 0; j0 < NTL * 16; j0 += 16) {
;         u32x4_t w[16]; float cj[16];
; #pragma unroll
;         for (int jj = 0; jj < 16; ++jj) { const u32x2_t pr = pl[j0 + jj]; const int ej = __builtin_amdgcn_readfirstlane((int)pr.x); cj[jj] = __uint_as_float(pr.y);
;             w[jj] = *(const u32x4_t*)(v8 + (size_t)ej * D + 16 * lane); }
; #pragma unroll
;         for (int jj = 0; jj < 16; ++jj) { const float c = cj[jj];
; #pragma unroll
;             for (int q = 0; q < 4; ++q) { const f32x2_t lo = __builtin_amdgcn_cvt_pk_f32_fp8((int)w[jj][q], false), hi = __builtin_amdgcn_cvt_pk_f32_fp8((int)w[jj][q], true);
;                 o[4 * q] += c * lo[0]; o[4 * q + 1] += c * lo[1]; o[4 * q + 2] += c * hi[0]; o[4 * q + 3] += c * hi[1]; } }
;     }
	v_cvt_pk_f32_fp8_e32 v[26:27], v160
	v_cvt_pk_f32_fp8_sdwa v[28:29], v160 src0_sel:WORD_1
	v_cvt_pk_f32_fp8_e32 v[30:31], v161
	v_cvt_pk_f32_fp8_sdwa v[32:33], v161 src0_sel:WORD_1
	v_cvt_pk_f32_fp8_e32 v[34:35], v162
	v_cvt_pk_f32_fp8_sdwa v[36:37], v162 src0_sel:WORD_1
	v_cvt_pk_f32_fp8_e32 v[38:39], v163
	v_cvt_pk_f32_fp8_sdwa v[40:41], v163 src0_sel:WORD_1
	v_cvt_pk_f32_fp8_e32 v[42:43], v164
	v_cvt_pk_f32_fp8_sdwa v[44:45], v164 src0_sel:WORD_1
	v_cvt_pk_f32_fp8_e32 v[46:47], v165
	v_cvt_pk_f32_fp8_sdwa v[48:49], v165 src0_sel:WORD_1
	v_cvt_pk_f32_fp8_e32 v[50:51], v166
	v_cvt_pk_f32_fp8_sdwa v[52:53], v166 src0_sel:WORD_1
	v_cvt_pk_f32_fp8_e32 v[54:55], v167
	v_cvt_pk_f32_fp8_sdwa v[56:57], v167 src0_sel:WORD_1
	global_load_dwordx4 v[160:163], v78, s[12:13]
	global_load_dwordx4 v[164:167], v79, s[12:13]
	v_pk_fma_f32 v[10:11], v[108:109], v[26:27], v[10:11] op_sel:[1,0,0]
	v_pk_fma_f32 v[12:13], v[108:109], v[28:29], v[12:13] op_sel:[1,0,0]
	v_pk_fma_f32 v[14:15], v[108:109], v[30:31], v[14:15] op_sel:[1,0,0]
	v_pk_fma_f32 v[16:17], v[108:109], v[32:33], v[16:17] op_sel:[1,0,0]
	v_pk_fma_f32 v[18:19], v[108:109], v[34:35], v[18:19] op_sel:[1,0,0]
	v_pk_fma_f32 v[20:21], v[108:109], v[36:37], v[20:21] op_sel:[1,0,0]
	v_pk_fma_f32 v[22:23], v[108:109], v[38:39], v[22:23] op_sel:[1,0,0]
	v_pk_fma_f32 v[24:25], v[108:109], v[40:41], v[24:25] op_sel:[1,0,0]
	v_pk_fma_f32 v[10:11], v[110:111], v[42:43], v[10:11] op_sel:[1,0,0]
	v_pk_fma_f32 v[12:13], v[110:111], v[44:45], v[12:13] op_sel:[1,0,0]
	v_pk_fma_f32 v[14:15], v[110:111], v[46:47], v[14:15] op_sel:[1,0,0]
	v_pk_fma_f32 v[16:17], v[110:111], v[48:49], v[16:17] op_sel:[1,0,0]
	v_pk_fma_f32 v[18:19], v[110:111], v[50:51], v[18:19] op_sel:[1,0,0]
	v_pk_fma_f32 v[20:21], v[110:111], v[52:53], v[20:21] op_sel:[1,0,0]
	v_pk_fma_f32 v[22:23], v[110:111], v[54:55], v[22:23] op_sel:[1,0,0]
	v_pk_fma_f32 v[24:25], v[110:111], v[56:57], v[24:25] op_sel:[1,0,0]
	s_waitcnt vmcnt(16)
	v_cvt_pk_f32_fp8_e32 v[26:27], v168
	v_cvt_pk_f32_fp8_sdwa v[28:29], v168 src0_sel:WORD_1
	v_cvt_pk_f32_fp8_e32 v[30:31], v169
	v_cvt_pk_f32_fp8_sdwa v[32:33], v169 src0_sel:WORD_1
	v_cvt_pk_f32_fp8_e32 v[34:35], v170
	v_cvt_pk_f32_fp8_sdwa v[36:37], v170 src0_sel:WORD_1
	v_cvt_pk_f32_fp8_e32 v[38:39], v171
	v_cvt_pk_f32_fp8_sdwa v[40:41], v171 src0_sel:WORD_1
	v_cvt_pk_f32_fp8_e32 v[42:43], v172
	v_cvt_pk_f32_fp8_sdwa v[44:45], v172 src0_sel:WORD_1
	v_cvt_pk_f32_fp8_e32 v[46:47], v173
	v_cvt_pk_f32_fp8_sdwa v[48:49], v173 src0_sel:WORD_1
	v_cvt_pk_f32_fp8_e32 v[50:51], v174
	v_cvt_pk_f32_fp8_sdwa v[52:53], v174 src0_sel:WORD_1
	v_cvt_pk_f32_fp8_e32 v[54:55], v175
	v_cvt_pk_f32_fp8_sdwa v[56:57], v175 src0_sel:WORD_1
	global_load_dwordx4 v[168:171], v80, s[12:13]
	global_load_dwordx4 v[172:175], v81, s[12:13]
	v_pk_fma_f32 v[10:11], v[112:113], v[26:27], v[10:11] op_sel:[1,0,0]
	v_pk_fma_f32 v[12:13], v[112:113], v[28:29], v[12:13] op_sel:[1,0,0]
	v_pk_fma_f32 v[14:15], v[112:113], v[30:31], v[14:15] op_sel:[1,0,0]
	v_pk_fma_f32 v[16:17], v[112:113], v[32:33], v[16:17] op_sel:[1,0,0]
	v_pk_fma_f32 v[18:19], v[112:113], v[34:35], v[18:19] op_sel:[1,0,0]
	v_pk_fma_f32 v[20:21], v[112:113], v[36:37], v[20:21] op_sel:[1,0,0]
	v_pk_fma_f32 v[22:23], v[112:113], v[38:39], v[22:23] op_sel:[1,0,0]
	v_pk_fma_f32 v[24:25], v[112:113], v[40:41], v[24:25] op_sel:[1,0,0]
	v_pk_fma_f32 v[10:11], v[114:115], v[42:43], v[10:11] op_sel:[1,0,0]
	v_pk_fma_f32 v[12:13], v[114:115], v[44:45], v[12:13] op_sel:[1,0,0]
	v_pk_fma_f32 v[14:15], v[114:115], v[46:47], v[14:15] op_sel:[1,0,0]
	v_pk_fma_f32 v[16:17], v[114:115], v[48:49], v[16:17] op_sel:[1,0,0]
	v_pk_fma_f32 v[18:19], v[114:115], v[50:51], v[18:19] op_sel:[1,0,0]
	v_pk_fma_f32 v[20:21], v[114:115], v[52:53], v[20:21] op_sel:[1,0,0]
	v_pk_fma_f32 v[22:23], v[114:115], v[54:55], v[22:23] op_sel:[1,0,0]
	v_pk_fma_f32 v[24:25], v[114:115], v[56:57], v[24:25] op_sel:[1,0,0]
	s_waitcnt vmcnt(16)
	v_cvt_pk_f32_fp8_e32 v[26:27], v188
	v_cvt_pk_f32_fp8_sdwa v[28:29], v188 src0_sel:WORD_1
	v_cvt_pk_f32_fp8_e32 v[30:31], v189
	v_cvt_pk_f32_fp8_sdwa v[32:33], v189 src0_sel:WORD_1
	v_cvt_pk_f32_fp8_e32 v[34:35], v190
	v_cvt_pk_f32_fp8_sdwa v[36:37], v190 src0_sel:WORD_1
	v_cvt_pk_f32_fp8_e32 v[38:39], v191
	v_cvt_pk_f32_fp8_sdwa v[40:41], v191 src0_sel:WORD_1
	v_cvt_pk_f32_fp8_e32 v[42:43], v192
	v_cvt_pk_f32_fp8_sdwa v[44:45], v192 src0_sel:WORD_1
	v_cvt_pk_f32_fp8_e32 v[46:47], v193
	v_cvt_pk_f32_fp8_sdwa v[48:49], v193 src0_sel:WORD_1
	v_cvt_pk_f32_fp8_e32 v[50:51], v194
	v_cvt_pk_f32_fp8_sdwa v[52:53], v194 src0_sel:WORD_1
	v_cvt_pk_f32_fp8_e32 v[54:55], v195
	v_cvt_pk_f32_fp8_sdwa v[56:57], v195 src0_sel:WORD_1
	global_load_dwordx4 v[188:191], v82, s[12:13]
	global_load_dwordx4 v[192:195], v83, s[12:13]
	v_pk_fma_f32 v[10:11], v[180:181], v[26:27], v[10:11] op_sel:[1,0,0]
	v_pk_fma_f32 v[12:13], v[180:181], v[28:29], v[12:13] op_sel:[1,0,0]
	v_pk_fma_f32 v[14:15], v[180:181], v[30:31], v[14:15] op_sel:[1,0,0]
	v_pk_fma_f32 v[16:17], v[180:181], v[32:33], v[16:17] op_sel:[1,0,0]
	v_pk_fma_f32 v[18:19], v[180:181], v[34:35], v[18:19] op_sel:[1,0,0]
	v_pk_fma_f32 v[20:21], v[180:181], v[36:37], v[20:21] op_sel:[1,0,0]
	v_pk_fma_f32 v[22:23], v[180:181], v[38:39], v[22:23] op_sel:[1,0,0]
	v_pk_fma_f32 v[24:25], v[180:181], v[40:41], v[24:25] op_sel:[1,0,0]
	v_pk_fma_f32 v[10:11], v[182:183], v[42:43], v[10:11] op_sel:[1,0,0]
	v_pk_fma_f32 v[12:13], v[182:183], v[44:45], v[12:13] op_sel:[1,0,0]
	v_pk_fma_f32 v[14:15], v[182:183], v[46:47], v[14:15] op_sel:[1,0,0]
	v_pk_fma_f32 v[16:17], v[182:183], v[48:49], v[16:17] op_sel:[1,0,0]
	v_pk_fma_f32 v[18:19], v[182:183], v[50:51], v[18:19] op_sel:[1,0,0]
	v_pk_fma_f32 v[20:21], v[182:183], v[52:53], v[20:21] op_sel:[1,0,0]
	v_pk_fma_f32 v[22:23], v[182:183], v[54:55], v[22:23] op_sel:[1,0,0]
	v_pk_fma_f32 v[24:25], v[182:183], v[56:57], v[24:25] op_sel:[1,0,0]
	s_nop 1
	v_permlane32_swap_b32_e32 v10, v18
	v_permlane32_swap_b32_e32 v11, v19
	v_permlane32_swap_b32_e32 v12, v20
	v_permlane32_swap_b32_e32 v13, v21
	v_permlane32_swap_b32_e32 v14, v22
	v_permlane32_swap_b32_e32 v15, v23
	v_permlane32_swap_b32_e32 v16, v24
	v_permlane32_swap_b32_e32 v17, v25
	v_add_f32_e32 v10, v10, v18
	v_add_f32_e32 v11, v11, v19
	v_add_f32_e32 v12, v12, v20
	v_add_f32_e32 v13, v13, v21
	v_add_f32_e32 v14, v14, v22
	v_add_f32_e32 v15, v15, v23
	v_add_f32_e32 v16, v16, v24
	v_add_f32_e32 v17, v17, v25
	s_nop 1
	v_permlane16_swap_b32_e32 v10, v14
	v_permlane16_swap_b32_e32 v11, v15
	v_permlane16_swap_b32_e32 v12, v16
	v_permlane16_swap_b32_e32 v13, v17
	v_add_f32_e32 v10, v10, v14
	v_add_f32_e32 v11, v11, v15
	v_add_f32_e32 v12, v12, v16
	v_add_f32_e32 v13, v13, v17
	v_cndmask_b32_e64 v14, v10, v12, s[24:25]
	v_cndmask_b32_e64 v16, v12, v10, s[24:25]
	v_cndmask_b32_e64 v15, v11, v13, s[24:25]
	v_cndmask_b32_e64 v17, v13, v11, s[24:25]
	s_nop 1
	v_add_f32_dpp v62, v16, v14 row_ror:8 row_mask:0xf bank_mask:0xf
	v_add_f32_dpp v63, v17, v15 row_ror:8 row_mask:0xf bank_mask:0xf
	s_waitcnt vmcnt(16)
; DEVI void adaln_apply_1(const P& p, int l, int r, int lane, float (&v)[16]) { adaln_apply<1>(p, l, r, lane, v); }
;     ...
;     const float* gp = gate2 + (size_t)row_seq(r) * 6144 + 16 * lane;
;     float* xp = x + (size_t)r * D + 16 * lane;
; #pragma unroll
;     for (int q = 0; q < 4; ++q) {
;         float4 xa = *(const float4*)(xp + 4 * q); const float4 ga = *(const float4*)(gp + 4 * q);
;         xa.x += ga.x * o[4 * q]; xa.y += ga.y * o[4 * q + 1]; xa.z += ga.z * o[4 * q + 2]; xa.w += ga.w * o[4 * q + 3];
;         *(float4*)(xp + 4 * q) = xa;
;         o[4 * q] = xa.x; o[4 * q + 1] = xa.y; o[4 * q + 2] = xa.z; o[4 * q + 3] = xa.w;
;     }
;     __builtin_amdgcn_sched_barrier(0);
;     if (l + 1 < DEPTH) adaln_apply_1(p, l + 1, r, lane, o);
	v_pk_fma_f32 v[58:59], v[62:63], v[60:61], v[58:59]
	global_store_dwordx2 v6, v[58:59], s[14:15]
	s_add_u32 s22, s22, 1
	s_cmp_lg_u32 s22, 64
	s_cbranch_scc1 .Lg2_loop
	s_waitcnt vmcnt(0)
	v_cmp_gt_u32_e32 vcc, 8, v116
	s_nop 1
	s_add_u32 s9, s8, 1
	s_mul_i32 s9, s9, 0xc000
	s_add_u32 s10, s6, 0x1f812100
	s_addc_u32 s11, s7, 0
	s_add_u32 s10, s10, s9
	s_addc_u32 s11, s11, 0
	s_lshr_b32 s12, s85, 13
	s_mul_i32 s12, s12, 0x1800
	v_lshlrev_b32_e32 v2, 4, v1
	v_add_u32_e32 v2, s12, v2
	v_add_u32_e32 v4, 0x1000, v2
	global_load_dwordx4 v[132:135], v2, s[10:11] offset:0
	global_load_dwordx4 v[136:139], v2, s[10:11] offset:1024
	global_load_dwordx4 v[140:143], v2, s[10:11] offset:2048
	global_load_dwordx4 v[144:147], v2, s[10:11] offset:3072
	global_load_dwordx4 v[148:151], v4, s[10:11] offset:0
	global_load_dwordx4 v[152:155], v4, s[10:11] offset:1024
	s_lshr_b32 s13, s12, 4
	v_add_u32_e32 v5, s13, v1
	v_mov_b32_e32 v12, 0x14100
	v_add_u32_e32 v6, 0, v5
	v_lshrrev_b32_e32 v3, 8, v6
	v_and_b32_e32 v13, 3, v6
	v_bfe_u32 v6, v6, 2, 6
	v_lshl_add_u32 v3, v3, 2, v13
	v_lshl_add_u32 v6, v3, 6, v6
	v_lshl_add_u32 v6, v6, 4, v12
	v_add_u32_e32 v7, 64, v5
	v_lshrrev_b32_e32 v3, 8, v7
	v_and_b32_e32 v13, 3, v7
	v_bfe_u32 v7, v7, 2, 6
	v_lshl_add_u32 v3, v3, 2, v13
	v_lshl_add_u32 v7, v3, 6, v7
	v_lshl_add_u32 v7, v7, 4, v12
	v_add_u32_e32 v8, 128, v5
	v_lshrrev_b32_e32 v3, 8, v8
	v_and_b32_e32 v13, 3, v8
	v_bfe_u32 v8, v8, 2, 6
	v_lshl_add_u32 v3, v3, 2, v13
	v_lshl_add_u32 v8, v3, 6, v8
	v_lshl_add_u32 v8, v8, 4, v12
	v_add_u32_e32 v9, 192, v5
	v_lshrrev_b32_e32 v3, 8, v9
	v_and_b32_e32 v13, 3, v9
	v_bfe_u32 v9, v9, 2, 6
	v_lshl_add_u32 v3, v3, 2, v13
	v_lshl_add_u32 v9, v3, 6, v9
	v_lshl_add_u32 v9, v9, 4, v12
	v_add_u32_e32 v10, 256, v5
	v_lshrrev_b32_e32 v3, 8, v10
	v_and_b32_e32 v13, 3, v10
	v_bfe_u32 v10, v10, 2, 6
	v_lshl_add_u32 v3, v3, 2, v13
	v_lshl_add_u32 v10, v3, 6, v10
	v_lshl_add_u32 v10, v10, 4, v12
	v_add_u32_e32 v11, 320, v5
	v_lshrrev_b32_e32 v3, 8, v11
	v_and_b32_e32 v13, 3, v11
	v_bfe_u32 v11, v11, 2, 6
	v_lshl_add_u32 v3, v3, 2, v13
	v_lshl_add_u32 v11, v3, 6, v11
	v_lshl_add_u32 v11, v11, 4, v12
	s_waitcnt vmcnt(0)
	ds_write_b128 v6, v[132:135]
	ds_write_b128 v7, v[136:139]
	ds_write_b128 v8, v[140:143]
	ds_write_b128 v9, v[144:147]
	ds_write_b128 v10, v[148:151]
	ds_write_b128 v11, v[152:155]
	s_waitcnt lgkmcnt(0)
	s_barrier
	s_ashr_i32 s9, s8, 31
	s_lshl_b64 s[18:19], s[8:9], 24
	s_lshl_b64 s[10:11], s[8:9], 16
	s_add_u32 s9, s6, s10
	s_addc_u32 s13, s7, s11
	s_add_u32 s10, s9, 0x2fa42100
	s_addc_u32 s11, s13, 0
	s_add_u32 s12, s9, 0x2fa82100
	s_addc_u32 s13, s13, 0
	s_add_u32 s14, s6, 0x1b292100
	s_addc_u32 s15, s7, 0
	s_add_u32 s16, s6, 0x1bb12100
	s_addc_u32 s17, s7, 0
	s_add_u32 s18, s6, s18
	s_addc_u32 s19, s7, s19
	v_lshl_add_u64 v[2:3], s[18:19], 0, v[102:103]
	s_mov_b64 s[20:21], 0x1fa42100
	v_lshl_add_u64 v[104:105], v[2:3], 0, s[20:21]
	v_mov_b32_e32 v2, 0x1100000
	v_cndmask_b32_e64 v66, v2, 0, vcc
	v_lshl_add_u64 v[2:3], s[6:7], 0, v[66:67]
	s_add_u32 s49, s6, 0x4000
	v_lshl_add_u64 v[2:3], v[2:3], 0, v[102:103]
	s_mov_b64 s[20:21], 0x2fac2100
	s_addc_u32 s50, s7, 0
	v_lshl_add_u64 v[106:107], v[2:3], 0, s[20:21]
	s_add_u32 s20, s49, s47
	v_lshl_add_u64 v[2:3], s[18:19], 0, v[100:101]
	s_mov_b64 s[18:19], 0x27a42100
	s_addc_u32 s21, s50, s46
	v_lshl_add_u64 v[108:109], v[2:3], 0, s[18:19]
	v_lshlrev_b64 v[2:3], 2, v[100:101]
	v_lshl_add_u64 v[4:5], s[20:21], 0, v[2:3]
	s_mov_b64 s[18:19], 0x5000
	s_cmp_lt_i32 s8, 3
	v_lshl_add_u64 v[110:111], v[4:5], 0, s[18:19]
	s_cselect_b64 s[18:19], -1, 0
	s_add_i32 s24, s8, 1
	s_ashr_i32 s25, s24, 31
	s_lshl_b64 s[20:21], s[24:25], 12
	s_add_u32 s55, s6, 0x20e100
	s_addc_u32 s56, s7, 0
	s_lshl_b32 s26, s24, 2
	s_ashr_i32 s27, s26, 31
	s_mul_i32 s23, s24, 0xc000
	s_mul_hi_i32 s22, s24, 0xc000
	s_add_u32 s23, s6, s23
	s_addc_u32 s28, s7, s22
	s_add_u32 s22, s23, 0x1f812100
	s_addc_u32 s23, s28, 0
	s_add_u32 s57, s6, 0xcb8a100
	s_addc_u32 s58, s7, 0
	s_lshl_b64 s[28:29], s[24:25], 18
	s_add_u32 s59, s4, s28
	s_addc_u32 s60, s5, s29
	s_lshl_b32 s28, s24, 3
	s_ashr_i32 s29, s28, 31
	s_add_u32 s61, s6, 0xacda100
	s_mov_b32 s9, 0
	v_lshl_add_u64 v[112:113], s[4:5], 0, v[2:3]
	s_mul_hi_i32 s51, s24, 18
	s_mul_i32 s54, s24, 18
	s_addc_u32 s62, s7, 0
	s_lshl_b64 s[24:25], s[26:27], 2
	s_lshl_b64 s[26:27], s[28:29], 2
	s_mov_b32 s63, s48
	s_branch .LBB0_1087

;     DEVI float* mod() const { return (float*)(ws + WS_MOD); }
;     DEVI float* rstd() const { return (float*)(ws + WS_RSTD); }
; DEVI cfp_t inp(int i) { const __attribute__((address_space(4))) cfp_t* k = (const __attribute__((address_space(4))) cfp_t*)__builtin_amdgcn_kernarg_segment_ptr(); typedef const __attribute__((address_space(1))) float* gcfp_t; const gcfp_t r = *(const volatile __attribute__((address_space(4))) gcfp_t*)(k + i); return (cfp_t)r; }
; template <int WHICH> DEVI void adaln_apply(const P& p, int l, int r, int lane_in, float (&v)[16]) {
;     int lane = lane_in; asm volatile("" : "+v"(lane));
;     const float* g = inp(WHICH == 1 ? 9 : 10) + (size_t)l * D + 16 * lane;
;     const int osh = (WHICH == 1 ? 0 : 3) * D, osc = (WHICH == 1 ? 1 : 4) * D;
;     float ss = 0.f;
; #pragma unroll
;     for (int i = 0; i < 16; ++i) ss += v[i] * v[i];
;     const float rstd = rsqrtf(wave_sum(ss) * (1.f / D) + EPS);
;     const float* md = p.mod() + ((size_t)l * NSEQ + row_seq(r)) * 6144 + 16 * lane;
; #pragma unroll
;     for (int q = 0; q < 4; ++q) {
;         const float4 gg = *(const float4*)(g + 4 * q), sc = *(const float4*)(md + osc + 4 * q), sh = *(const float4*)(md + osh + 4 * q);
;         v[4 * q] = v[4 * q] * rstd * gg.x * (1.f + sc.x) + sh.x; v[4 * q + 1] = v[4 * q + 1] * rstd * gg.y * (1.f + sc.y) + sh.y;
;         v[4 * q + 2] = v[4 * q + 2] * rstd * gg.z * (1.f + sc.z) + sh.z; v[4 * q + 3] = v[4 * q + 3] * rstd * gg.w * (1.f + sc.w) + sh.w;
;     }
.LBB0_1111:
	s_add_i32 s28, s64, s9
	s_mul_i32 s28, s28, s34
	s_add_i32 s28, s28, s48
	s_cmpk_gt_i32 s28, 0x3fff
	s_cbranch_scc1 .LBB0_1110
	v_mov_b32_e32 v114, 0
	s_mov_b32 s29, -16
	s_mov_b32 s30, s65
	v_mov_b32_e32 v115, v114
	v_mov_b32_e32 v120, v114
	v_mov_b32_e32 v121, v114
	v_mov_b32_e32 v118, v114
	v_mov_b32_e32 v119, v114
	v_mov_b32_e32 v128, v114
	v_mov_b32_e32 v129, v114
	v_mov_b32_e32 v130, v114
	v_mov_b32_e32 v131, v114
	v_mov_b32_e32 v122, v114
	v_mov_b32_e32 v123, v114
	v_mov_b32_e32 v124, v114
	v_mov_b32_e32 v125, v114
	v_mov_b32_e32 v126, v114
	v_mov_b32_e32 v127, v114
	s_ashr_i32 s29, s28, 31
	s_lshr_b32 s30, s29, 19
	s_add_i32 s30, s28, s30
	s_ashr_i32 s30, s30, 13
	s_lshl_b64 s[40:41], s[28:29], 12
	s_nop 0
	v_lshl_add_u64 v[16:17], v[112:113], 0, s[40:41]
	global_load_dwordx4 v[30:33], v[16:17], off sc1
	global_load_dwordx4 v[22:25], v[16:17], off offset:16 sc1
	global_load_dwordx4 v[26:29], v[16:17], off offset:32 sc1
	global_load_dwordx4 v[18:21], v[16:17], off offset:48 sc1
	s_waitcnt vmcnt(0)
	s_and_b64 vcc, exec, s[18:19]
	s_cbranch_vccz .LBB0_1110
	v_pk_mul_f32 v[2:3], v[30:31], v[30:31]
	v_pk_mul_f32 v[4:5], v[32:33], v[32:33]
	v_add_f32_e32 v2, v2, v3
	v_add_f32_e32 v2, v4, v2
	v_pk_mul_f32 v[6:7], v[22:23], v[22:23]
	v_add_f32_e32 v2, v5, v2
	v_add_f32_e32 v2, v2, v6
	v_pk_mul_f32 v[8:9], v[24:25], v[24:25]
	v_add_f32_e32 v2, v7, v2
	v_add_f32_e32 v2, v8, v2
	v_pk_mul_f32 v[10:11], v[26:27], v[26:27]
	v_add_f32_e32 v2, v9, v2
	v_add_f32_e32 v2, v2, v10
	v_pk_mul_f32 v[12:13], v[28:29], v[28:29]
	v_add_f32_e32 v2, v11, v2
	v_add_f32_e32 v2, v12, v2
	v_pk_mul_f32 v[14:15], v[18:19], v[18:19]
	v_add_f32_e32 v2, v13, v2
	v_add_f32_e32 v2, v2, v14
	v_pk_mul_f32 v[16:17], v[20:21], v[20:21]
	v_add_f32_e32 v2, v15, v2
	v_add_f32_e32 v2, v16, v2
	v_add_f32_e32 v4, v17, v2
	ds_bpermute_b32 v5, v179, v4
	v_mov_b32_e32 v58, v1
	s_load_dwordx2 s[40:41], s[0:1], 0x48
	s_ashr_i32 s31, s30, 31
	s_waitcnt lgkmcnt(0)
	v_add_f32_e32 v4, v4, v5
	ds_bpermute_b32 v5, v204, v4
	v_lshlrev_b32_e32 v60, 4, v58
	v_ashrrev_i32_e32 v61, 31, v60
	s_add_u32 s40, s40, s20
	s_addc_u32 s41, s41, s21
	s_waitcnt lgkmcnt(0)
	v_add_f32_e32 v4, v4, v5
	ds_bpermute_b32 v5, v205, v4
	v_lshlrev_b64 v[62:63], 2, v[60:61]
	v_lshl_add_u64 v[2:3], s[40:41], 0, v[62:63]
	s_mov_b32 s40, 0x800000
	s_add_u32 s30, s54, s30
	s_waitcnt lgkmcnt(0)
	v_add_f32_e32 v4, v4, v5
	ds_bpermute_b32 v5, v206, v4
	s_addc_u32 s31, s51, s31
	s_mulk_i32 s31, 0x6000
	s_mov_b64 s[42:43], 0x1000
	global_load_dwordx4 v[34:37], v[2:3], off offset:48
	global_load_dwordx4 v[38:41], v[2:3], off offset:32
	global_load_dwordx4 v[50:53], v[2:3], off offset:16
	global_load_dwordx4 v[68:71], v[2:3], off
	s_waitcnt lgkmcnt(0)
	v_add_f32_e32 v4, v4, v5
	ds_bpermute_b32 v5, v207, v4
	s_waitcnt lgkmcnt(0)
	v_add_f32_e32 v4, v4, v5
	ds_bpermute_b32 v5, v208, v4
	s_waitcnt lgkmcnt(0)
	v_add_f32_e32 v4, v4, v5
	v_fmamk_f32 v4, v4, 0x3a800000, v211
	v_cmp_gt_f32_e32 vcc, s40, v4
	v_mul_f32_e32 v5, 0x4b800000, v4
	s_mul_hi_u32 s40, s30, 0x6000
	v_cndmask_b32_e32 v4, v4, v5, vcc
	v_rsq_f32_e32 v4, v4
	s_add_i32 s40, s40, s31
	s_mulk_i32 s30, 0x6000
	s_add_u32 s30, s49, s30
	s_addc_u32 s31, s50, s40
	v_mul_f32_e32 v5, 0x45800000, v4
	v_lshl_add_u64 v[14:15], s[30:31], 0, v[62:63]
	s_movk_i32 s30, 0x1000
	v_cndmask_b32_e32 v59, v4, v5, vcc
	v_add_co_u32_e32 v2, vcc, s30, v14
	v_lshl_add_u64 v[4:5], v[14:15], 0, s[42:43]
	s_nop 0
	v_addc_co_u32_e32 v3, vcc, 0, v15, vcc
	global_load_dwordx4 v[72:75], v[2:3], off
	global_load_dwordx4 v[42:45], v[4:5], off offset:48
	global_load_dwordx4 v[46:49], v[4:5], off offset:32
	global_load_dwordx4 v[54:57], v[4:5], off offset:16
	s_nop 0
	global_load_dwordx4 v[2:5], v[14:15], off offset:48
	global_load_dwordx4 v[6:9], v[14:15], off offset:32
	global_load_dwordx4 v[10:13], v[14:15], off offset:16
	s_nop 0
	global_load_dwordx4 v[14:17], v[14:15], off
	v_mul_f32_e32 v30, v30, v59
	v_mul_f32_e32 v22, v22, v59
	s_lshl_b64 s[30:31], s[28:29], 11
	s_add_u32 s30, s55, s30
	s_addc_u32 s31, s56, s31
	s_waitcnt vmcnt(9)
	v_mul_f32_e32 v22, v22, v50
	s_waitcnt vmcnt(8)
	v_mul_f32_e32 v30, v68, v30
	s_waitcnt vmcnt(7)
	v_add_f32_e32 v64, 1.0, v72
	s_waitcnt vmcnt(0)
	v_fma_f32 v14, v64, v30, v14
	v_mul_f32_e32 v30, v31, v59
	v_mul_f32_e32 v30, v69, v30
	v_add_f32_e32 v31, 1.0, v73
	v_fma_f32 v15, v31, v30, v15
	v_mul_f32_e32 v30, v32, v59
	v_mul_f32_e32 v30, v70, v30
	v_add_f32_e32 v31, 1.0, v74
	v_fma_f32 v16, v31, v30, v16
	v_mul_f32_e32 v30, v33, v59
	v_mul_f32_e32 v30, v71, v30
	v_add_f32_e32 v31, 1.0, v75
	v_fmac_f32_e32 v17, v31, v30
	v_add_f32_e32 v30, 1.0, v54
	v_fma_f32 v50, v22, v30, v10
	v_mul_f32_e32 v10, v23, v59
	v_mul_f32_e32 v10, v10, v51
	v_add_f32_e32 v22, 1.0, v55
	v_fma_f32 v51, v10, v22, v11
	v_mul_f32_e32 v10, v24, v59
	v_mul_f32_e32 v10, v10, v52
	v_add_f32_e32 v11, 1.0, v56
	v_fma_f32 v12, v10, v11, v12
	v_mul_f32_e32 v10, v25, v59
	v_mul_f32_e32 v10, v10, v53
	v_add_f32_e32 v11, 1.0, v57
	v_fmac_f32_e32 v13, v10, v11
	v_mul_f32_e32 v10, v26, v59
	v_mul_f32_e32 v10, v10, v38
	v_add_f32_e32 v11, 1.0, v46
	v_fma_f32 v38, v10, v11, v6
	v_mul_f32_e32 v6, v27, v59
	v_mul_f32_e32 v6, v6, v39
	v_add_f32_e32 v10, 1.0, v47
	v_fma_f32 v39, v6, v10, v7
	v_mul_f32_e32 v6, v28, v59
	v_mul_f32_e32 v6, v6, v40
	v_add_f32_e32 v7, 1.0, v48
	v_fma_f32 v40, v6, v7, v8
	v_mul_f32_e32 v6, v29, v59
	v_mul_f32_e32 v6, v6, v41
	v_add_f32_e32 v7, 1.0, v49
	v_fmac_f32_e32 v9, v6, v7
	v_mul_f32_e32 v6, v18, v59
	v_mul_f32_e32 v6, v6, v34
	v_add_f32_e32 v7, 1.0, v42
	v_fma_f32 v34, v6, v7, v2
	v_mul_f32_e32 v2, v19, v59
	v_mul_f32_e32 v2, v2, v35
	v_add_f32_e32 v6, 1.0, v43
;     DEVI float* rstd() const { return (float*)(ws + WS_RSTD); }
;     DEVI bf16_t* hb() const { return (bf16_t*)(ws + WS_HB); }
;     DEVI float* wsmall() const { return (float*)(ws + WS_WSMALL); }
; DEVI unsigned pk2bf(float lo, float hi) { unsigned r; asm volatile("v_cvt_pk_bf16_f32 %0, %1, %2" : "=v"(r) : "v"(lo), "v"(hi)); return r; }
; template <int WHICH> DEVI void adaln_apply(const P& p, int l, int r, int lane_in, float (&v)[16]) {
;     ...
;         v[4 * q] = v[4 * q] * rstd * gg.x * (1.f + sc.x) + sh.x; v[4 * q + 1] = v[4 * q + 1] * rstd * gg.y * (1.f + sc.y) + sh.y;
;         v[4 * q + 2] = v[4 * q + 2] * rstd * gg.z * (1.f + sc.z) + sh.z; v[4 * q + 3] = v[4 * q + 3] * rstd * gg.w * (1.f + sc.w) + sh.w;
;     }
;     u32x4_t* ob = (u32x4_t*)(p.hb() + (size_t)r * D + 16 * lane);
;     ob[0] = (u32x4_t){pk2bf(v[0], v[1]), pk2bf(v[2], v[3]), pk2bf(v[4], v[5]), pk2bf(v[6], v[7])};
;     ob[1] = (u32x4_t){pk2bf(v[8], v[9]), pk2bf(v[10], v[11]), pk2bf(v[12], v[13]), pk2bf(v[14], v[15])};
;     if constexpr (WHICH == 2) {
;         unsigned hi8[4], lo8[4];
; #pragma unroll
;         for (int q = 0; q < 4; ++q) { hi8[q] = pk4fp8(v[4 * q], v[4 * q + 1], v[4 * q + 2], v[4 * q + 3]);
;             const f32x2_t h01 = __builtin_amdgcn_cvt_pk_f32_fp8((int)hi8[q], false), h23 = __builtin_amdgcn_cvt_pk_f32_fp8((int)hi8[q], true);
;             lo8[q] = pk4fp8((v[4 * q] - h01[0]) * 32.f, (v[4 * q + 1] - h01[1]) * 32.f, (v[4 * q + 2] - h23[0]) * 32.f, (v[4 * q + 3] - h23[1]) * 32.f); }
;         *(u32x4_t*)(p.h8() + (size_t)r * D + 16 * lane) = (u32x4_t){hi8[0], hi8[1], hi8[2], hi8[3]};
;         *(u32x4_t*)(p.h8() + (size_t)M * D + (size_t)r * D + 16 * lane) = (u32x4_t){lo8[0], lo8[1], lo8[2], lo8[3]};
;     }
;     if constexpr (WHICH == 1) {
;         const float* dtb = inp(16) + l * 8; const float* fb = inp(22) + l * 4;
;         const float* ws = p.wsmall() + (size_t)l * 12 * D + 16 * lane;
;         float dot[12];
; #pragma unroll
;         for (int jj = 0; jj < 12; ++jj) { float a = 0.f;
; #pragma unroll
;             for (int q = 0; q < 4; ++q) { const float4 w = *(const float4*)(ws + (size_t)jj * D + 4 * q); a += v[4 * q] * w.x + v[4 * q + 1] * w.y + v[4 * q + 2] * w.z + v[4 * q + 3] * w.w; }
;             dot[jj] = wave_sum(a); }
	v_fma_f32 v35, v2, v6, v3
	v_mul_f32_e32 v2, v20, v59
	v_mul_f32_e32 v2, v2, v36
	v_add_f32_e32 v3, 1.0, v44
	v_fma_f32 v36, v2, v3, v4
	v_mul_f32_e32 v2, v21, v59
	v_mul_f32_e32 v2, v2, v37
	v_add_f32_e32 v3, 1.0, v45
	v_fmac_f32_e32 v5, v2, v3
	v_lshl_add_u64 v[2:3], v[60:61], 1, s[30:31]
	v_cvt_pk_bf16_f32 v18, v14, v15
	v_cvt_pk_bf16_f32 v19, v16, v17
	v_cvt_pk_bf16_f32 v20, v50, v51
	v_cvt_pk_bf16_f32 v21, v12, v13
	global_store_dwordx4 v[2:3], v[18:21], off
	s_nop 1
	v_cvt_pk_bf16_f32 v18, v38, v39
	v_cvt_pk_bf16_f32 v19, v40, v9
	v_cvt_pk_bf16_f32 v20, v34, v35
	v_cvt_pk_bf16_f32 v21, v36, v5
	global_store_dwordx4 v[2:3], v[18:21], off offset:16
	v_mov_b32_e32 v91, 0x14100
	v_lshl_add_u32 v90, v58, 4, v91
	v_mov_b32_e32 v88, 0
	v_mov_b32_e32 v89, 0
	ds_read_b128 v[132:135], v90 offset:0
	ds_read_b128 v[136:139], v90 offset:1024
	ds_read_b128 v[140:143], v90 offset:2048
	ds_read_b128 v[144:147], v90 offset:3072
	ds_read_b128 v[148:151], v90 offset:4096
	ds_read_b128 v[152:155], v90 offset:5120
	ds_read_b128 v[156:159], v90 offset:6144
	ds_read_b128 v[160:163], v90 offset:7168
	ds_read_b128 v[164:167], v90 offset:8192
	ds_read_b128 v[168:171], v90 offset:9216
	ds_read_b128 v[172:175], v90 offset:10240
	ds_read_b128 v[180:183], v90 offset:11264
	ds_read_b128 v[184:187], v90 offset:12288
	ds_read_b128 v[188:191], v90 offset:13312
	ds_read_b128 v[192:195], v90 offset:14336
	ds_read_b128 v[196:199], v90 offset:15360
	s_waitcnt lgkmcnt(0)
	v_mov_b32_e32 v216, v40
	v_mov_b32_e32 v217, v9
	v_mov_b32_e32 v218, v36
	v_mov_b32_e32 v219, v5
	v_pk_mul_f32 v[92:93], v[14:15], v[132:133]
	v_pk_mul_f32 v[94:95], v[14:15], v[148:149]
	v_pk_mul_f32 v[96:97], v[14:15], v[164:165]
	v_pk_mul_f32 v[98:99], v[14:15], v[184:185]
	v_pk_fma_f32 v[92:93], v[16:17], v[134:135], v[92:93]
	v_pk_fma_f32 v[94:95], v[16:17], v[150:151], v[94:95]
	v_pk_fma_f32 v[96:97], v[16:17], v[166:167], v[96:97]
	v_pk_fma_f32 v[98:99], v[16:17], v[186:187], v[98:99]
	v_pk_fma_f32 v[92:93], v[50:51], v[136:137], v[92:93]
	v_pk_fma_f32 v[94:95], v[50:51], v[152:153], v[94:95]
	v_pk_fma_f32 v[96:97], v[50:51], v[168:169], v[96:97]
	v_pk_fma_f32 v[98:99], v[50:51], v[188:189], v[98:99]
	v_pk_fma_f32 v[92:93], v[12:13], v[138:139], v[92:93]
	v_pk_fma_f32 v[94:95], v[12:13], v[154:155], v[94:95]
	v_pk_fma_f32 v[96:97], v[12:13], v[170:171], v[96:97]
	v_pk_fma_f32 v[98:99], v[12:13], v[190:191], v[98:99]
	v_pk_fma_f32 v[92:93], v[38:39], v[140:141], v[92:93]
	v_pk_fma_f32 v[94:95], v[38:39], v[156:157], v[94:95]
	v_pk_fma_f32 v[96:97], v[38:39], v[172:173], v[96:97]
	v_pk_fma_f32 v[98:99], v[38:39], v[192:193], v[98:99]
	v_pk_fma_f32 v[92:93], v[216:217], v[142:143], v[92:93]
	v_pk_fma_f32 v[94:95], v[216:217], v[158:159], v[94:95]
	v_pk_fma_f32 v[96:97], v[216:217], v[174:175], v[96:97]
	v_pk_fma_f32 v[98:99], v[216:217], v[194:195], v[98:99]
	v_pk_fma_f32 v[92:93], v[34:35], v[144:145], v[92:93]
	v_pk_fma_f32 v[94:95], v[34:35], v[160:161], v[94:95]
	v_pk_fma_f32 v[96:97], v[34:35], v[180:181], v[96:97]
	v_pk_fma_f32 v[98:99], v[34:35], v[196:197], v[98:99]
	v_pk_fma_f32 v[92:93], v[218:219], v[146:147], v[92:93]
	v_pk_fma_f32 v[94:95], v[218:219], v[162:163], v[94:95]
	v_pk_fma_f32 v[96:97], v[218:219], v[182:183], v[96:97]
	v_pk_fma_f32 v[98:99], v[218:219], v[198:199], v[98:99]
	v_add_f32_e32 v76, v92, v93
	v_add_f32_e32 v77, v94, v95
	v_add_f32_e32 v78, v96, v97
	v_add_f32_e32 v79, v98, v99
	ds_read_b128 v[132:135], v90 offset:16384
	ds_read_b128 v[136:139], v90 offset:17408
	ds_read_b128 v[140:143], v90 offset:18432
	ds_read_b128 v[144:147], v90 offset:19456
	ds_read_b128 v[148:151], v90 offset:20480
	ds_read_b128 v[152:155], v90 offset:21504
	ds_read_b128 v[156:159], v90 offset:22528
	ds_read_b128 v[160:163], v90 offset:23552
	ds_read_b128 v[164:167], v90 offset:24576
	ds_read_b128 v[168:171], v90 offset:25600
	ds_read_b128 v[172:175], v90 offset:26624
	ds_read_b128 v[180:183], v90 offset:27648
	ds_read_b128 v[184:187], v90 offset:28672
	ds_read_b128 v[188:191], v90 offset:29696
	ds_read_b128 v[192:195], v90 offset:30720
	ds_read_b128 v[196:199], v90 offset:31744
	s_waitcnt lgkmcnt(0)
	v_pk_mul_f32 v[92:93], v[14:15], v[132:133]
	v_pk_mul_f32 v[94:95], v[14:15], v[148:149]
	v_pk_mul_f32 v[96:97], v[14:15], v[164:165]
	v_pk_mul_f32 v[98:99], v[14:15], v[184:185]
	v_pk_fma_f32 v[92:93], v[16:17], v[134:135], v[92:93]
	v_pk_fma_f32 v[94:95], v[16:17], v[150:151], v[94:95]
	v_pk_fma_f32 v[96:97], v[16:17], v[166:167], v[96:97]
	v_pk_fma_f32 v[98:99], v[16:17], v[186:187], v[98:99]
	v_pk_fma_f32 v[92:93], v[50:51], v[136:137], v[92:93]
	v_pk_fma_f32 v[94:95], v[50:51], v[152:153], v[94:95]
	v_pk_fma_f32 v[96:97], v[50:51], v[168:169], v[96:97]
	v_pk_fma_f32 v[98:99], v[50:51], v[188:189], v[98:99]
	v_pk_fma_f32 v[92:93], v[12:13], v[138:139], v[92:93]
	v_pk_fma_f32 v[94:95], v[12:13], v[154:155], v[94:95]
	v_pk_fma_f32 v[96:97], v[12:13], v[170:171], v[96:97]
	v_pk_fma_f32 v[98:99], v[12:13], v[190:191], v[98:99]
	v_pk_fma_f32 v[92:93], v[38:39], v[140:141], v[92:93]
	v_pk_fma_f32 v[94:95], v[38:39], v[156:157], v[94:95]
	v_pk_fma_f32 v[96:97], v[38:39], v[172:173], v[96:97]
	v_pk_fma_f32 v[98:99], v[38:39], v[192:193], v[98:99]
	v_pk_fma_f32 v[92:93], v[216:217], v[142:143], v[92:93]
	v_pk_fma_f32 v[94:95], v[216:217], v[158:159], v[94:95]
	v_pk_fma_f32 v[96:97], v[216:217], v[174:175], v[96:97]
	v_pk_fma_f32 v[98:99], v[216:217], v[194:195], v[98:99]
	v_pk_fma_f32 v[92:93], v[34:35], v[144:145], v[92:93]
	v_pk_fma_f32 v[94:95], v[34:35], v[160:161], v[94:95]
	v_pk_fma_f32 v[96:97], v[34:35], v[180:181], v[96:97]
	v_pk_fma_f32 v[98:99], v[34:35], v[196:197], v[98:99]
	v_pk_fma_f32 v[92:93], v[218:219], v[146:147], v[92:93]
	v_pk_fma_f32 v[94:95], v[218:219], v[162:163], v[94:95]
	v_pk_fma_f32 v[96:97], v[218:219], v[182:183], v[96:97]
	v_pk_fma_f32 v[98:99], v[218:219], v[198:199], v[98:99]
	v_add_f32_e32 v80, v92, v93
	v_add_f32_e32 v81, v94, v95
	v_add_f32_e32 v82, v96, v97
	v_add_f32_e32 v83, v98, v99
	ds_read_b128 v[132:135], v90 offset:32768
	ds_read_b128 v[136:139], v90 offset:33792
	ds_read_b128 v[140:143], v90 offset:34816
	ds_read_b128 v[144:147], v90 offset:35840
	ds_read_b128 v[148:151], v90 offset:36864
	ds_read_b128 v[152:155], v90 offset:37888
	ds_read_b128 v[156:159], v90 offset:38912
	ds_read_b128 v[160:163], v90 offset:39936
	ds_read_b128 v[164:167], v90 offset:40960
	ds_read_b128 v[168:171], v90 offset:41984
	ds_read_b128 v[172:175], v90 offset:43008
	ds_read_b128 v[180:183], v90 offset:44032
	ds_read_b128 v[184:187], v90 offset:45056
	ds_read_b128 v[188:191], v90 offset:46080
	ds_read_b128 v[192:195], v90 offset:47104
	ds_read_b128 v[196:199], v90 offset:48128
	s_waitcnt lgkmcnt(0)
; DEVI float wave_sum(float v) {
; #pragma unroll
;     for (int o = 1; o < 64; o <<= 1) v += __shfl_xor(v, o);
;     return v;
; }
; template <int WHICH> DEVI void adaln_apply(const P& p, int l, int r, int lane_in, float (&v)[16]) {
;     ...
;         float dot[12];
; #pragma unroll
;         for (int jj = 0; jj < 12; ++jj) { float a = 0.f;
; #pragma unroll
;             for (int q = 0; q < 4; ++q) { const float4 w = *(const float4*)(ws + (size_t)jj * D + 4 * q); a += v[4 * q] * w.x + v[4 * q + 1] * w.y + v[4 * q + 2] * w.z + v[4 * q + 3] * w.w; }
;             dot[jj] = wave_sum(a); }
	v_pk_mul_f32 v[92:93], v[14:15], v[132:133]
	v_pk_mul_f32 v[94:95], v[14:15], v[148:149]
	v_pk_mul_f32 v[96:97], v[14:15], v[164:165]
	v_pk_mul_f32 v[98:99], v[14:15], v[184:185]
	v_pk_fma_f32 v[92:93], v[16:17], v[134:135], v[92:93]
	v_pk_fma_f32 v[94:95], v[16:17], v[150:151], v[94:95]
	v_pk_fma_f32 v[96:97], v[16:17], v[166:167], v[96:97]
	v_pk_fma_f32 v[98:99], v[16:17], v[186:187], v[98:99]
	v_pk_fma_f32 v[92:93], v[50:51], v[136:137], v[92:93]
	v_pk_fma_f32 v[94:95], v[50:51], v[152:153], v[94:95]
	v_pk_fma_f32 v[96:97], v[50:51], v[168:169], v[96:97]
	v_pk_fma_f32 v[98:99], v[50:51], v[188:189], v[98:99]
	v_pk_fma_f32 v[92:93], v[12:13], v[138:139], v[92:93]
	v_pk_fma_f32 v[94:95], v[12:13], v[154:155], v[94:95]
	v_pk_fma_f32 v[96:97], v[12:13], v[170:171], v[96:97]
	v_pk_fma_f32 v[98:99], v[12:13], v[190:191], v[98:99]
	v_pk_fma_f32 v[92:93], v[38:39], v[140:141], v[92:93]
	v_pk_fma_f32 v[94:95], v[38:39], v[156:157], v[94:95]
	v_pk_fma_f32 v[96:97], v[38:39], v[172:173], v[96:97]
	v_pk_fma_f32 v[98:99], v[38:39], v[192:193], v[98:99]
	v_pk_fma_f32 v[92:93], v[216:217], v[142:143], v[92:93]
	v_pk_fma_f32 v[94:95], v[216:217], v[158:159], v[94:95]
	v_pk_fma_f32 v[96:97], v[216:217], v[174:175], v[96:97]
	v_pk_fma_f32 v[98:99], v[216:217], v[194:195], v[98:99]
	v_pk_fma_f32 v[92:93], v[34:35], v[144:145], v[92:93]
	v_pk_fma_f32 v[94:95], v[34:35], v[160:161], v[94:95]
	v_pk_fma_f32 v[96:97], v[34:35], v[180:181], v[96:97]
	v_pk_fma_f32 v[98:99], v[34:35], v[196:197], v[98:99]
	v_pk_fma_f32 v[92:93], v[218:219], v[146:147], v[92:93]
	v_pk_fma_f32 v[94:95], v[218:219], v[162:163], v[94:95]
	v_pk_fma_f32 v[96:97], v[218:219], v[182:183], v[96:97]
	v_pk_fma_f32 v[98:99], v[218:219], v[198:199], v[98:99]
	v_add_f32_e32 v84, v92, v93
	v_add_f32_e32 v85, v94, v95
	v_add_f32_e32 v86, v96, v97
	v_add_f32_e32 v87, v98, v99
	s_nop 1
	v_add_f32_dpp v76, v76, v76 quad_perm:[1,0,3,2] row_mask:0xf bank_mask:0xf
	v_add_f32_dpp v77, v77, v77 quad_perm:[1,0,3,2] row_mask:0xf bank_mask:0xf
	v_add_f32_dpp v78, v78, v78 quad_perm:[1,0,3,2] row_mask:0xf bank_mask:0xf
	v_add_f32_dpp v79, v79, v79 quad_perm:[1,0,3,2] row_mask:0xf bank_mask:0xf
	v_add_f32_dpp v80, v80, v80 quad_perm:[1,0,3,2] row_mask:0xf bank_mask:0xf
	v_add_f32_dpp v81, v81, v81 quad_perm:[1,0,3,2] row_mask:0xf bank_mask:0xf
	v_add_f32_dpp v82, v82, v82 quad_perm:[1,0,3,2] row_mask:0xf bank_mask:0xf
	v_add_f32_dpp v83, v83, v83 quad_perm:[1,0,3,2] row_mask:0xf bank_mask:0xf
	v_add_f32_dpp v84, v84, v84 quad_perm:[1,0,3,2] row_mask:0xf bank_mask:0xf
	v_add_f32_dpp v85, v85, v85 quad_perm:[1,0,3,2] row_mask:0xf bank_mask:0xf
	v_add_f32_dpp v86, v86, v86 quad_perm:[1,0,3,2] row_mask:0xf bank_mask:0xf
	v_add_f32_dpp v87, v87, v87 quad_perm:[1,0,3,2] row_mask:0xf bank_mask:0xf
	v_add_f32_dpp v76, v76, v76 quad_perm:[2,3,0,1] row_mask:0xf bank_mask:0xf
	v_add_f32_dpp v77, v77, v77 quad_perm:[2,3,0,1] row_mask:0xf bank_mask:0xf
	v_add_f32_dpp v78, v78, v78 quad_perm:[2,3,0,1] row_mask:0xf bank_mask:0xf
	v_add_f32_dpp v79, v79, v79 quad_perm:[2,3,0,1] row_mask:0xf bank_mask:0xf
	v_add_f32_dpp v80, v80, v80 quad_perm:[2,3,0,1] row_mask:0xf bank_mask:0xf
	v_add_f32_dpp v81, v81, v81 quad_perm:[2,3,0,1] row_mask:0xf bank_mask:0xf
	v_add_f32_dpp v82, v82, v82 quad_perm:[2,3,0,1] row_mask:0xf bank_mask:0xf
	v_add_f32_dpp v83, v83, v83 quad_perm:[2,3,0,1] row_mask:0xf bank_mask:0xf
	v_add_f32_dpp v84, v84, v84 quad_perm:[2,3,0,1] row_mask:0xf bank_mask:0xf
	v_add_f32_dpp v85, v85, v85 quad_perm:[2,3,0,1] row_mask:0xf bank_mask:0xf
	v_add_f32_dpp v86, v86, v86 quad_perm:[2,3,0,1] row_mask:0xf bank_mask:0xf
	v_add_f32_dpp v87, v87, v87 quad_perm:[2,3,0,1] row_mask:0xf bank_mask:0xf
	v_add_f32_dpp v76, v76, v76 row_half_mirror row_mask:0xf bank_mask:0xf
	v_add_f32_dpp v77, v77, v77 row_half_mirror row_mask:0xf bank_mask:0xf
	v_add_f32_dpp v78, v78, v78 row_half_mirror row_mask:0xf bank_mask:0xf
	v_add_f32_dpp v79, v79, v79 row_half_mirror row_mask:0xf bank_mask:0xf
	v_add_f32_dpp v80, v80, v80 row_half_mirror row_mask:0xf bank_mask:0xf
	v_add_f32_dpp v81, v81, v81 row_half_mirror row_mask:0xf bank_mask:0xf
	v_add_f32_dpp v82, v82, v82 row_half_mirror row_mask:0xf bank_mask:0xf
	v_add_f32_dpp v83, v83, v83 row_half_mirror row_mask:0xf bank_mask:0xf
	v_add_f32_dpp v84, v84, v84 row_half_mirror row_mask:0xf bank_mask:0xf
	v_add_f32_dpp v85, v85, v85 row_half_mirror row_mask:0xf bank_mask:0xf
	v_add_f32_dpp v86, v86, v86 row_half_mirror row_mask:0xf bank_mask:0xf
	v_add_f32_dpp v87, v87, v87 row_half_mirror row_mask:0xf bank_mask:0xf
	v_add_f32_dpp v76, v76, v76 row_mirror row_mask:0xf bank_mask:0xf
	v_add_f32_dpp v77, v77, v77 row_mirror row_mask:0xf bank_mask:0xf
	v_add_f32_dpp v78, v78, v78 row_mirror row_mask:0xf bank_mask:0xf
	v_add_f32_dpp v79, v79, v79 row_mirror row_mask:0xf bank_mask:0xf
	v_add_f32_dpp v80, v80, v80 row_mirror row_mask:0xf bank_mask:0xf
	v_add_f32_dpp v81, v81, v81 row_mirror row_mask:0xf bank_mask:0xf
	v_add_f32_dpp v82, v82, v82 row_mirror row_mask:0xf bank_mask:0xf
	v_add_f32_dpp v83, v83, v83 row_mirror row_mask:0xf bank_mask:0xf
	v_add_f32_dpp v84, v84, v84 row_mirror row_mask:0xf bank_mask:0xf
	v_add_f32_dpp v85, v85, v85 row_mirror row_mask:0xf bank_mask:0xf
	v_add_f32_dpp v86, v86, v86 row_mirror row_mask:0xf bank_mask:0xf
	v_add_f32_dpp v87, v87, v87 row_mirror row_mask:0xf bank_mask:0xf
	v_add_f32_dpp v76, v76, v76 row_bcast:15 row_mask:0xa bank_mask:0xf
	v_add_f32_dpp v77, v77, v77 row_bcast:15 row_mask:0xa bank_mask:0xf
	v_add_f32_dpp v78, v78, v78 row_bcast:15 row_mask:0xa bank_mask:0xf
	v_add_f32_dpp v79, v79, v79 row_bcast:15 row_mask:0xa bank_mask:0xf
;     DEVI float* dt() const { return (float*)(ws + WS_DT); }
;     DEVI float* logf() const { return (float*)(ws + WS_LOGF); }
; DEVI float softplus_f(float x) { return x > 20.f ? x : log1pf(expf(x)); }
; template <int WHICH> DEVI void adaln_apply(const P& p, int l, int r, int lane_in, float (&v)[16]) {
;     ...
;             dot[jj] = wave_sum(a); }
;         if (lane < 8) {
;             float d = dot[0];
; #pragma unroll
;             for (int jj = 1; jj < 8; ++jj) d = (lane == jj) ? dot[jj] : d;
;             p.dt()[(size_t)r * 8 + lane] = softplus_f(d + dtb[lane]);
;         } else if (lane < 12) {
;             const int hd = lane - 8; float d = dot[8];
; #pragma unroll
;             for (int jj = 9; jj < 12; ++jj) d = (lane == jj) ? dot[jj] : d;
;             const float lf = -softplus_f(-(d + fb[hd]));
;             p.logf()[(size_t)r * 4 + hd] = lf;
;             if (r < M_P) p.out[OUT_LFP + ((size_t)l * M_P + r) * 4 + hd] = lf; else p.out[OUT_LFS + ((size_t)l * M_S + (r - M_P)) * 4 + hd] = lf;
;         }
	v_add_f32_dpp v80, v80, v80 row_bcast:15 row_mask:0xa bank_mask:0xf
	v_add_f32_dpp v81, v81, v81 row_bcast:15 row_mask:0xa bank_mask:0xf
	v_add_f32_dpp v82, v82, v82 row_bcast:15 row_mask:0xa bank_mask:0xf
	v_add_f32_dpp v83, v83, v83 row_bcast:15 row_mask:0xa bank_mask:0xf
	v_add_f32_dpp v84, v84, v84 row_bcast:15 row_mask:0xa bank_mask:0xf
	v_add_f32_dpp v85, v85, v85 row_bcast:15 row_mask:0xa bank_mask:0xf
	v_add_f32_dpp v86, v86, v86 row_bcast:15 row_mask:0xa bank_mask:0xf
	v_add_f32_dpp v87, v87, v87 row_bcast:15 row_mask:0xa bank_mask:0xf
	v_add_f32_dpp v76, v76, v76 row_bcast:31 row_mask:0xc bank_mask:0xf
	v_add_f32_dpp v77, v77, v77 row_bcast:31 row_mask:0xc bank_mask:0xf
	v_add_f32_dpp v78, v78, v78 row_bcast:31 row_mask:0xc bank_mask:0xf
	v_add_f32_dpp v79, v79, v79 row_bcast:31 row_mask:0xc bank_mask:0xf
	v_add_f32_dpp v80, v80, v80 row_bcast:31 row_mask:0xc bank_mask:0xf
	v_add_f32_dpp v81, v81, v81 row_bcast:31 row_mask:0xc bank_mask:0xf
	v_add_f32_dpp v82, v82, v82 row_bcast:31 row_mask:0xc bank_mask:0xf
	v_add_f32_dpp v83, v83, v83 row_bcast:31 row_mask:0xc bank_mask:0xf
	v_add_f32_dpp v84, v84, v84 row_bcast:31 row_mask:0xc bank_mask:0xf
	v_add_f32_dpp v85, v85, v85 row_bcast:31 row_mask:0xc bank_mask:0xf
	v_add_f32_dpp v86, v86, v86 row_bcast:31 row_mask:0xc bank_mask:0xf
	v_add_f32_dpp v87, v87, v87 row_bcast:31 row_mask:0xc bank_mask:0xf
	s_nop 1
	v_readlane_b32 s30, v76, 63
	v_readlane_b32 s31, v77, 63
	v_readlane_b32 s40, v78, 63
	v_readlane_b32 s41, v79, 63
	v_readlane_b32 s42, v80, 63
	v_readlane_b32 s43, v81, 63
	s_nop 1
	v_writelane_b32 v88, s30, 0
	v_writelane_b32 v88, s31, 1
	v_writelane_b32 v88, s40, 2
	v_writelane_b32 v88, s41, 3
	v_writelane_b32 v88, s42, 4
	v_writelane_b32 v88, s43, 5
	v_readlane_b32 s30, v82, 63
	v_readlane_b32 s31, v83, 63
	v_readlane_b32 s40, v84, 63
	v_readlane_b32 s41, v85, 63
	v_readlane_b32 s42, v86, 63
	v_readlane_b32 s43, v87, 63
	s_nop 1
	v_writelane_b32 v88, s30, 6
	v_writelane_b32 v88, s31, 7
	v_writelane_b32 v88, s40, 8
	v_writelane_b32 v88, s41, 9
	v_writelane_b32 v88, s42, 10
	v_writelane_b32 v88, s43, 11
	v_mov_b32_e32 v4, v88
	v_mov_b32_e32 v37, v88
	v_mov_b32_e32 v42, v88
	v_mov_b32_e32 v44, v88
	v_mov_b32_e32 v46, v88
	v_mov_b32_e32 v48, v88
	v_mov_b32_e32 v52, v88
	v_mov_b32_e32 v54, v88
	v_mov_b32_e32 v56, v88
	v_mov_b32_e32 v6, v88
	v_mov_b32_e32 v10, v88
	v_mov_b32_e32 v2, v88
	v_mov_b32_e32 v8, v89
	v_mov_b32_e32 v41, v89
	v_mov_b32_e32 v43, v89
	v_mov_b32_e32 v45, v89
	v_mov_b32_e32 v47, v89
	v_mov_b32_e32 v49, v89
	v_mov_b32_e32 v53, v89
	v_mov_b32_e32 v55, v89
	v_mov_b32_e32 v57, v89
	v_mov_b32_e32 v7, v89
	v_mov_b32_e32 v11, v89
	v_mov_b32_e32 v3, v89
	s_load_dwordx2 s[30:31], s[0:1], 0x80
	s_load_dwordx2 s[40:41], s[0:1], 0xb0
	s_waitcnt lgkmcnt(0)
	v_cmp_lt_i32_e32 vcc, 7, v58
	s_nop 3
	s_and_saveexec_b64 s[42:43], vcc
	s_xor_b64 s[42:43], exec, s[42:43]
	s_cbranch_execz .LBB0_1121
	v_cmp_gt_u32_e32 vcc, 12, v58
	s_and_saveexec_b64 s[44:45], vcc
	s_cbranch_execz .LBB0_1120
	s_add_u32 s40, s40, s24
	s_addc_u32 s41, s41, s25
	v_add_u32_e32 v66, -8, v58
	v_lshl_add_u64 v[4:5], v[66:67], 2, s[40:41]
	global_load_dword v4, v[4:5], off
	v_add_f32_e32 v5, v56, v57
	v_add_f32_e32 v6, v6, v7
	v_cmp_eq_u32_e32 vcc, 9, v58
	v_add_f32_e32 v7, v10, v11
	s_waitcnt lgkmcnt(0)
	v_add_f32_e32 v2, v2, v3
	v_cndmask_b32_e32 v3, v5, v6, vcc
	v_cmp_eq_u32_e32 vcc, 10, v58
	s_mov_b32 s40, 0xc1a00000
	s_nop 0
	v_cndmask_b32_e32 v3, v3, v7, vcc
	v_cmp_eq_u32_e32 vcc, 11, v58
	s_nop 1
	v_cndmask_b32_e32 v2, v3, v2, vcc
	s_waitcnt vmcnt(0)
	v_add_f32_e32 v2, v2, v4
	v_xor_b32_e32 v3, 0x80000000, v2
	v_cmp_ngt_f32_e32 vcc, s40, v2
	s_and_saveexec_b64 s[40:41], vcc
	s_cbranch_execz .LBB0_1119
;     DEVI float* logf() const { return (float*)(ws + WS_LOGF); }
; DEVI float silu_f(float x) { return x / (1.f + expf(-x)); }
; DEVI float softplus_f(float x) { return x > 20.f ? x : log1pf(expf(x)); }
; template <int WHICH> DEVI void adaln_apply(const P& p, int l, int r, int lane_in, float (&v)[16]) {
;     ...
;         } else if (lane < 12) {
;             const int hd = lane - 8; float d = dot[8];
; #pragma unroll
;             for (int jj = 9; jj < 12; ++jj) d = (lane == jj) ? dot[jj] : d;
;             const float lf = -softplus_f(-(d + fb[hd]));
;             p.logf()[(size_t)r * 4 + hd] = lf;
	v_mul_f32_e32 v3, 0xbfb8aa3b, v2
	v_rndne_f32_e32 v4, v3
	s_mov_b32 s66, 0xbfb8aa3b
	v_sub_f32_e32 v5, v3, v4
	v_fma_f32 v3, v2, s66, -v3
	v_fmac_f32_e32 v3, 0xb2a5705f, v2
	v_add_f32_e32 v3, v5, v3
	v_cvt_i32_f32_e32 v4, v4
	v_exp_f32_e32 v3, v3
	s_mov_b32 s66, 0x42ce8ed0
	v_cmp_nlt_f32_e32 vcc, s66, v2
	s_mov_b32 s66, 0xc2b17218
	v_ldexp_f32 v3, v3, v4
	v_cndmask_b32_e32 v3, 0, v3, vcc
	v_cmp_ngt_f32_e32 vcc, s66, v2
	s_mov_b32 s66, 0x3f2aaaab
	s_nop 0
	v_cndmask_b32_e32 v16, v215, v3, vcc
	v_add_f32_e32 v4, 1.0, v16
	v_add_f32_e32 v2, -1.0, v4
	v_sub_f32_e32 v3, v2, v4
	v_add_f32_e32 v3, 1.0, v3
	v_sub_f32_e32 v2, v16, v2
	v_add_f32_e32 v5, v2, v3
	v_frexp_mant_f32_e32 v6, v4
	v_cvt_f64_f32_e32 v[2:3], v4
	v_frexp_exp_i32_f64_e32 v2, v[2:3]
	v_cmp_gt_f32_e32 vcc, s66, v6
	s_mov_b32 s66, 0x3f317218
	s_nop 0
	v_subbrev_co_u32_e32 v10, vcc, 0, v2, vcc
	v_sub_u32_e32 v2, 0, v10
	v_ldexp_f32 v3, v4, v2
	v_add_f32_e32 v4, -1.0, v3
	v_add_f32_e32 v6, 1.0, v3
	v_ldexp_f32 v2, v5, v2
	v_add_f32_e32 v5, 1.0, v4
	v_add_f32_e32 v7, -1.0, v6
	v_sub_f32_e32 v5, v3, v5
	v_sub_f32_e32 v3, v3, v7
	v_add_f32_e32 v5, v2, v5
	v_add_f32_e32 v2, v2, v3
	v_add_f32_e32 v11, v6, v2
	v_rcp_f32_e32 v13, v11
	v_sub_f32_e32 v3, v6, v11
	v_add_f32_e32 v12, v2, v3
	v_add_f32_e32 v3, v4, v5
	v_mul_f32_e32 v15, v3, v13
	v_sub_f32_e32 v2, v4, v3
	v_mul_f32_e32 v4, v11, v15
	v_fma_f32 v6, v15, v11, -v4
	v_fmac_f32_e32 v6, v15, v12
	v_add_f32_e32 v14, v5, v2
	v_add_f32_e32 v2, v4, v6
	v_sub_f32_e32 v5, v3, v2
	v_pk_add_f32 v[8:9], v[2:3], v[4:5] neg_lo:[0,1] neg_hi:[0,1]
	v_mov_b32_e32 v7, v2
	v_pk_add_f32 v[2:3], v[8:9], v[6:7] neg_lo:[0,1] neg_hi:[0,1]
	s_nop 0
	v_add_f32_e32 v3, v14, v3
	v_add_f32_e32 v2, v2, v3
	v_add_f32_e32 v3, v5, v2
	v_mul_f32_e32 v14, v13, v3
	v_mul_f32_e32 v4, v11, v14
	v_fma_f32 v6, v14, v11, -v4
	v_fmac_f32_e32 v6, v14, v12
	v_sub_f32_e32 v5, v5, v3
	v_add_f32_e32 v11, v2, v5
	v_add_f32_e32 v2, v4, v6
	v_sub_f32_e32 v5, v3, v2
	v_pk_add_f32 v[8:9], v[2:3], v[4:5] neg_lo:[0,1] neg_hi:[0,1]
	v_mov_b32_e32 v7, v2
	v_pk_add_f32 v[2:3], v[8:9], v[6:7] neg_lo:[0,1] neg_hi:[0,1]
	s_nop 0
	v_add_f32_e32 v3, v11, v3
	v_add_f32_e32 v2, v2, v3
	v_add_f32_e32 v3, v15, v14
	v_add_f32_e32 v2, v5, v2
	v_sub_f32_e32 v4, v3, v15
	v_mul_f32_e32 v2, v13, v2
	v_sub_f32_e32 v4, v14, v4
	v_add_f32_e32 v4, v4, v2
	v_add_f32_e32 v6, v3, v4
	v_mul_f32_e32 v7, v6, v6
	v_fmamk_f32 v2, v7, 0x3e9b6dac, v212
	v_fmaak_f32 v177, v7, v2, 0x3f2aaada
	v_cvt_f32_i32_e32 v2, v10
	v_sub_f32_e32 v3, v6, v3
	v_sub_f32_e32 v3, v4, v3
	v_ldexp_f32 v8, v3, 1
	v_mul_f32_e32 v3, v6, v7
	v_ldexp_f32 v5, v6, 1
	v_pk_mul_f32 v[6:7], v[2:3], v[176:177]
	s_nop 0
	v_fma_f32 v4, v2, s66, -v6
	v_fmac_f32_e32 v4, 0xb102e308, v2
	v_pk_add_f32 v[2:3], v[6:7], v[4:5]
	s_mov_b32 s66, 0x7f800000
	v_sub_f32_e32 v5, v3, v5
	v_sub_f32_e32 v5, v7, v5
	v_add_f32_e32 v9, v8, v5
	v_mov_b32_e32 v8, v6
	v_pk_add_f32 v[6:7], v[2:3], v[6:7] neg_lo:[0,1] neg_hi:[0,1]
	v_pk_add_f32 v[10:11], v[2:3], v[8:9]
	v_mov_b32_e32 v5, v2
	v_mov_b32_e32 v7, v11
	v_pk_add_f32 v[12:13], v[4:5], v[6:7] neg_lo:[0,1] neg_hi:[0,1]
	v_pk_add_f32 v[4:5], v[4:5], v[6:7]
	v_mov_b32_e32 v8, v9
	v_pk_add_f32 v[6:7], v[4:5], v[2:3] op_sel:[1,0] op_sel_hi:[0,1] neg_lo:[0,1] neg_hi:[0,1]
	v_pk_add_f32 v[14:15], v[10:11], v[6:7] op_sel_hi:[1,0] neg_lo:[0,1] neg_hi:[0,1]
	v_mov_b32_e32 v10, v11
	v_mov_b32_e32 v11, v5
	v_pk_mov_b32 v[6:7], v[2:3], v[6:7] op_sel:[1,0]
	v_mov_b32_e32 v9, v2
	v_pk_add_f32 v[6:7], v[10:11], v[6:7] neg_lo:[0,1] neg_hi:[0,1]
	v_mov_b32_e32 v14, v12
	v_pk_add_f32 v[2:3], v[8:9], v[6:7] neg_lo:[0,1] neg_hi:[0,1]
	v_mov_b32_e32 v13, v5
	v_pk_add_f32 v[6:7], v[14:15], v[2:3]
	v_cmp_neq_f32_e32 vcc, s66, v16
	v_pk_add_f32 v[8:9], v[6:7], v[6:7] op_sel:[0,1] op_sel_hi:[1,0]
	s_mov_b32 s66, 0x33800000
	v_pk_add_f32 v[4:5], v[4:5], v[8:9] op_sel:[1,0] op_sel_hi:[0,1]
	v_mov_b32_e32 v7, v4
	v_pk_add_f32 v[10:11], v[6:7], v[12:13] neg_lo:[0,1] neg_hi:[0,1]
	v_mov_b32_e32 v3, v8
	v_sub_f32_e32 v5, v6, v10
	v_pk_add_f32 v[2:3], v[2:3], v[10:11] neg_lo:[0,1] neg_hi:[0,1]
	v_sub_f32_e32 v5, v12, v5
	v_add_f32_e32 v2, v2, v5
	v_add_f32_e32 v2, v2, v3
	v_add_f32_e32 v2, v4, v2
	v_cndmask_b32_e32 v2, v215, v2, vcc
	v_cmp_lt_f32_e64 vcc, |v16|, s66
	s_nop 1
	v_cndmask_b32_e32 v3, v2, v16, vcc
